# GEMM mainloops: serpentine MFMA order (one operand fragment changes per MFMA) on top of v29
# speedup vs baseline: 1.0079x; 1.0079x over previous
.LBB0_226:
	ds_read_b128 v[144:147], v151
	ds_read_b128 v[154:157], v151 offset:1024
	ds_read_b128 v[158:161], v151 offset:2048
	ds_read_b128 v[162:165], v151 offset:3072
	ds_read_b128 v[166:169], v152
	ds_read_b128 v[170:173], v152 offset:1024
	ds_read_b128 v[174:177], v152 offset:2048
	ds_read_b128 v[178:181], v152 offset:3072
	s_add_u32 s26, s24, 0xfff80080
	s_addc_u32 s27, s25, -1
	s_cmp_eq_u32 s60, 28
	s_cselect_b32 s29, s17, s27
	s_cselect_b32 s28, s54, s26
	s_cselect_b32 s27, s15, s59
	s_cselect_b32 s26, s55, s58
	v_lshl_add_u64 v[190:191], s[24:25], 0, v[136:137]
	s_add_i32 m0, s23, 0xc000
	ds_read_b128 v[182:185], v153
	ds_read_b128 v[186:189], v153 offset:1024
	ds_read_b128 v[194:197], v153 offset:2048
	ds_read_b128 v[198:201], v153 offset:3072
	ds_read_b128 v[202:205], v153 offset:4096
	ds_read_b128 v[206:209], v153 offset:5120
	ds_read_b128 v[210:213], v153 offset:6144
	ds_read_b128 v[214:217], v153 offset:7168
	global_load_lds_dwordx4 v[190:191], off
	v_lshl_add_u64 v[190:191], s[24:25], 0, v[138:139]
	s_add_i32 m0, s23, 0xe000
	s_nop 0
	global_load_lds_dwordx4 v[190:191], off
	s_waitcnt vmcnt(8)
	s_waitcnt lgkmcnt(0)
	s_barrier
	s_waitcnt lgkmcnt(0)
	v_mfma_f32_16x16x32_bf16 v[124:127], v[144:147], v[182:185], v[124:127]
	v_mfma_f32_16x16x32_bf16 v[120:123], v[158:161], v[182:185], v[120:123]
	v_mfma_f32_16x16x32_bf16 v[108:111], v[158:161], v[194:197], v[108:111]
	v_mfma_f32_16x16x32_bf16 v[116:119], v[144:147], v[194:197], v[116:119]
	v_mfma_f32_16x16x32_bf16 v[100:103], v[144:147], v[202:205], v[100:103]
	v_mfma_f32_16x16x32_bf16 v[92:95], v[158:161], v[202:205], v[92:95]
	v_mfma_f32_16x16x32_bf16 v[76:79], v[158:161], v[210:213], v[76:79]
	v_mfma_f32_16x16x32_bf16 v[84:87], v[144:147], v[210:213], v[84:87]
	v_mfma_f32_16x16x32_bf16 v[124:127], v[154:157], v[186:189], v[124:127]
	v_mfma_f32_16x16x32_bf16 v[120:123], v[162:165], v[186:189], v[120:123]
	v_mfma_f32_16x16x32_bf16 v[108:111], v[162:165], v[198:201], v[108:111]
	v_mfma_f32_16x16x32_bf16 v[116:119], v[154:157], v[198:201], v[116:119]
	v_mfma_f32_16x16x32_bf16 v[100:103], v[154:157], v[206:209], v[100:103]
	v_mfma_f32_16x16x32_bf16 v[92:95], v[162:165], v[206:209], v[92:95]
	v_mfma_f32_16x16x32_bf16 v[76:79], v[162:165], v[214:217], v[76:79]
	v_mfma_f32_16x16x32_bf16 v[84:87], v[154:157], v[214:217], v[84:87]
	v_mfma_f32_16x16x32_bf16 v[112:115], v[166:169], v[182:185], v[112:115]
	v_mfma_f32_16x16x32_bf16 v[104:107], v[174:177], v[182:185], v[104:107]
	v_mfma_f32_16x16x32_bf16 v[88:91], v[174:177], v[194:197], v[88:91]
	v_mfma_f32_16x16x32_bf16 v[96:99], v[166:169], v[194:197], v[96:99]
	v_mfma_f32_16x16x32_bf16 v[80:83], v[166:169], v[202:205], v[80:83]
	v_mfma_f32_16x16x32_bf16 v[72:75], v[174:177], v[202:205], v[72:75]
	v_mfma_f32_16x16x32_bf16 v[64:67], v[174:177], v[210:213], v[64:67]
	v_mfma_f32_16x16x32_bf16 v[68:71], v[166:169], v[210:213], v[68:71]
	v_mfma_f32_16x16x32_bf16 v[112:115], v[170:173], v[186:189], v[112:115]
	v_mfma_f32_16x16x32_bf16 v[104:107], v[178:181], v[186:189], v[104:107]
	v_mfma_f32_16x16x32_bf16 v[88:91], v[178:181], v[198:201], v[88:91]
	v_mfma_f32_16x16x32_bf16 v[96:99], v[170:173], v[198:201], v[96:99]
	v_mfma_f32_16x16x32_bf16 v[80:83], v[170:173], v[206:209], v[80:83]
	v_mfma_f32_16x16x32_bf16 v[72:75], v[178:181], v[206:209], v[72:75]
	v_mfma_f32_16x16x32_bf16 v[64:67], v[178:181], v[214:217], v[64:67]
	v_mfma_f32_16x16x32_bf16 v[68:71], v[170:173], v[214:217], v[68:71]
	s_barrier
	s_add_i32 s33, s48, s36
	v_lshl_add_u64 v[190:191], s[26:27], 0, v[132:133]
	s_mov_b32 m0, s33
	ds_read_b128 v[182:185], v153 offset:16384
	ds_read_b128 v[186:189], v153 offset:17408
	ds_read_b128 v[194:197], v153 offset:18432
	ds_read_b128 v[198:201], v153 offset:19456
	ds_read_b128 v[202:205], v153 offset:20480
	ds_read_b128 v[206:209], v153 offset:21504
	ds_read_b128 v[210:213], v153 offset:22528
	ds_read_b128 v[214:217], v153 offset:23552
	global_load_lds_dwordx4 v[190:191], off
	s_add_i32 m0, s33, 0x2000
	s_add_u32 s62, s26, 0x80000
	v_lshl_add_u64 v[218:219], s[26:27], 0, v[128:129]
	s_addc_u32 s63, s27, 0
	s_add_i32 s33, s49, s36
	global_load_lds_dwordx4 v[218:219], off
	v_lshl_add_u64 v[220:221], s[62:63], 0, v[132:133]
	s_mov_b32 m0, s33
	v_lshl_add_u64 v[222:223], s[28:29], 0, v[130:131]
	global_load_lds_dwordx4 v[220:221], off
	v_lshl_add_u64 v[220:221], s[62:63], 0, v[128:129]
	s_add_i32 m0, s33, 0x2000
	s_nop 0
	global_load_lds_dwordx4 v[220:221], off
	v_lshl_add_u64 v[220:221], s[28:29], 0, v[134:135]
	s_mov_b32 m0, s23
	s_nop 0
	global_load_lds_dwordx4 v[220:221], off
	s_mov_b32 m0, s38
	s_nop 0
	global_load_lds_dwordx4 v[222:223], off
	s_waitcnt vmcnt(8)
	s_waitcnt lgkmcnt(0)
	s_barrier
	s_waitcnt lgkmcnt(0)
	v_mfma_f32_16x16x32_bf16 v[60:63], v[144:147], v[182:185], v[60:63]
	v_mfma_f32_16x16x32_bf16 v[56:59], v[158:161], v[182:185], v[56:59]
	v_mfma_f32_16x16x32_bf16 v[44:47], v[158:161], v[194:197], v[44:47]
	v_mfma_f32_16x16x32_bf16 v[52:55], v[144:147], v[194:197], v[52:55]
	v_mfma_f32_16x16x32_bf16 v[36:39], v[144:147], v[202:205], v[36:39]
	v_mfma_f32_16x16x32_bf16 v[28:31], v[158:161], v[202:205], v[28:31]
	v_mfma_f32_16x16x32_bf16 v[12:15], v[158:161], v[210:213], v[12:15]
	v_mfma_f32_16x16x32_bf16 v[20:23], v[144:147], v[210:213], v[20:23]
	v_mfma_f32_16x16x32_bf16 v[60:63], v[154:157], v[186:189], v[60:63]
	v_mfma_f32_16x16x32_bf16 v[56:59], v[162:165], v[186:189], v[56:59]
	v_mfma_f32_16x16x32_bf16 v[44:47], v[162:165], v[198:201], v[44:47]
	v_mfma_f32_16x16x32_bf16 v[52:55], v[154:157], v[198:201], v[52:55]
	v_mfma_f32_16x16x32_bf16 v[36:39], v[154:157], v[206:209], v[36:39]
	v_mfma_f32_16x16x32_bf16 v[28:31], v[162:165], v[206:209], v[28:31]
	v_mfma_f32_16x16x32_bf16 v[12:15], v[162:165], v[214:217], v[12:15]
	v_mfma_f32_16x16x32_bf16 v[20:23], v[154:157], v[214:217], v[20:23]
	v_mfma_f32_16x16x32_bf16 v[48:51], v[166:169], v[182:185], v[48:51]
	v_mfma_f32_16x16x32_bf16 v[40:43], v[174:177], v[182:185], v[40:43]
	v_mfma_f32_16x16x32_bf16 v[24:27], v[174:177], v[194:197], v[24:27]
	v_mfma_f32_16x16x32_bf16 v[32:35], v[166:169], v[194:197], v[32:35]
	v_mfma_f32_16x16x32_bf16 v[16:19], v[166:169], v[202:205], v[16:19]
	v_mfma_f32_16x16x32_bf16 v[8:11], v[174:177], v[202:205], v[8:11]
	v_mfma_f32_16x16x32_bf16 v[0:3], v[174:177], v[210:213], v[0:3]
	v_mfma_f32_16x16x32_bf16 v[4:7], v[166:169], v[210:213], v[4:7]
	v_mfma_f32_16x16x32_bf16 v[48:51], v[170:173], v[186:189], v[48:51]
	v_mfma_f32_16x16x32_bf16 v[40:43], v[178:181], v[186:189], v[40:43]
	v_mfma_f32_16x16x32_bf16 v[24:27], v[178:181], v[198:201], v[24:27]
	v_mfma_f32_16x16x32_bf16 v[32:35], v[170:173], v[198:201], v[32:35]
	v_mfma_f32_16x16x32_bf16 v[16:19], v[170:173], v[206:209], v[16:19]
	v_mfma_f32_16x16x32_bf16 v[8:11], v[178:181], v[206:209], v[8:11]
	v_mfma_f32_16x16x32_bf16 v[0:3], v[178:181], v[214:217], v[0:3]
	v_mfma_f32_16x16x32_bf16 v[4:7], v[170:173], v[214:217], v[4:7]
	s_barrier
	s_add_i32 s33, 0, 0x18000
	s_add_i32 s56, 0, 0x1c000
	v_add_u32_e32 v162, s33, v149
	v_add_u32_e32 v178, s56, v149
	ds_read_b128 v[144:147], v162
	ds_read_b128 v[154:157], v162 offset:1024
	ds_read_b128 v[158:161], v162 offset:2048
	ds_read_b128 v[162:165], v162 offset:3072
	ds_read_b128 v[166:169], v178
	ds_read_b128 v[170:173], v178 offset:1024
	ds_read_b128 v[174:177], v178 offset:2048
	ds_read_b128 v[178:181], v178 offset:3072
	s_add_u32 s28, s28, 0x80000
	s_addc_u32 s29, s29, 0
	s_mov_b32 m0, s39
	v_lshl_add_u64 v[224:225], s[28:29], 0, v[134:135]
	ds_read_b128 v[182:185], v153 offset:32768
	ds_read_b128 v[186:189], v153 offset:33792
	ds_read_b128 v[194:197], v153 offset:34816
	ds_read_b128 v[198:201], v153 offset:35840
	ds_read_b128 v[202:205], v153 offset:36864
	ds_read_b128 v[206:209], v153 offset:37888
	ds_read_b128 v[210:213], v153 offset:38912
	ds_read_b128 v[214:217], v153 offset:39936
	global_load_lds_dwordx4 v[224:225], off
	v_lshl_add_u64 v[224:225], s[28:29], 0, v[130:131]
	s_mov_b32 m0, s40
	s_nop 0
	global_load_lds_dwordx4 v[224:225], off
	s_waitcnt vmcnt(8)
	s_waitcnt lgkmcnt(0)
	s_barrier
	s_waitcnt lgkmcnt(0)
	v_mfma_f32_16x16x32_bf16 v[124:127], v[144:147], v[182:185], v[124:127]
	v_mfma_f32_16x16x32_bf16 v[120:123], v[158:161], v[182:185], v[120:123]
	v_mfma_f32_16x16x32_bf16 v[108:111], v[158:161], v[194:197], v[108:111]
	v_mfma_f32_16x16x32_bf16 v[116:119], v[144:147], v[194:197], v[116:119]
	v_mfma_f32_16x16x32_bf16 v[100:103], v[144:147], v[202:205], v[100:103]
	v_mfma_f32_16x16x32_bf16 v[92:95], v[158:161], v[202:205], v[92:95]
	v_mfma_f32_16x16x32_bf16 v[76:79], v[158:161], v[210:213], v[76:79]
	v_mfma_f32_16x16x32_bf16 v[84:87], v[144:147], v[210:213], v[84:87]
	v_mfma_f32_16x16x32_bf16 v[124:127], v[154:157], v[186:189], v[124:127]
	v_mfma_f32_16x16x32_bf16 v[120:123], v[162:165], v[186:189], v[120:123]
	v_mfma_f32_16x16x32_bf16 v[108:111], v[162:165], v[198:201], v[108:111]
	v_mfma_f32_16x16x32_bf16 v[116:119], v[154:157], v[198:201], v[116:119]
	v_mfma_f32_16x16x32_bf16 v[100:103], v[154:157], v[206:209], v[100:103]
	v_mfma_f32_16x16x32_bf16 v[92:95], v[162:165], v[206:209], v[92:95]
	v_mfma_f32_16x16x32_bf16 v[76:79], v[162:165], v[214:217], v[76:79]
	v_mfma_f32_16x16x32_bf16 v[84:87], v[154:157], v[214:217], v[84:87]
	v_mfma_f32_16x16x32_bf16 v[112:115], v[166:169], v[182:185], v[112:115]
	v_mfma_f32_16x16x32_bf16 v[104:107], v[174:177], v[182:185], v[104:107]
	v_mfma_f32_16x16x32_bf16 v[88:91], v[174:177], v[194:197], v[88:91]
	v_mfma_f32_16x16x32_bf16 v[96:99], v[166:169], v[194:197], v[96:99]
	v_mfma_f32_16x16x32_bf16 v[80:83], v[166:169], v[202:205], v[80:83]
	v_mfma_f32_16x16x32_bf16 v[72:75], v[174:177], v[202:205], v[72:75]
	v_mfma_f32_16x16x32_bf16 v[64:67], v[174:177], v[210:213], v[64:67]
	v_mfma_f32_16x16x32_bf16 v[68:71], v[166:169], v[210:213], v[68:71]
	v_mfma_f32_16x16x32_bf16 v[112:115], v[170:173], v[186:189], v[112:115]
	v_mfma_f32_16x16x32_bf16 v[104:107], v[178:181], v[186:189], v[104:107]
	v_mfma_f32_16x16x32_bf16 v[88:91], v[178:181], v[198:201], v[88:91]
	v_mfma_f32_16x16x32_bf16 v[96:99], v[170:173], v[198:201], v[96:99]
	v_mfma_f32_16x16x32_bf16 v[80:83], v[170:173], v[206:209], v[80:83]
	v_mfma_f32_16x16x32_bf16 v[72:75], v[178:181], v[206:209], v[72:75]
	v_mfma_f32_16x16x32_bf16 v[64:67], v[178:181], v[214:217], v[64:67]
	v_mfma_f32_16x16x32_bf16 v[68:71], v[170:173], v[214:217], v[68:71]
	s_barrier
	s_add_i32 s28, s33, s36
	v_lshl_add_u64 v[190:191], v[190:191], 0, s[10:11]
	s_mov_b32 m0, s28
	ds_read_b128 v[182:185], v153 offset:49152
	ds_read_b128 v[186:189], v153 offset:50176
	ds_read_b128 v[194:197], v153 offset:51200
	ds_read_b128 v[198:201], v153 offset:52224
	ds_read_b128 v[202:205], v153 offset:53248
	ds_read_b128 v[206:209], v153 offset:54272
	ds_read_b128 v[210:213], v153 offset:55296
	ds_read_b128 v[214:217], v153 offset:56320
	global_load_lds_dwordx4 v[190:191], off
	s_add_i32 m0, s28, 0x2000
	s_add_u32 s26, s26, 0x80080
	v_lshl_add_u64 v[190:191], v[218:219], 0, s[10:11]
	s_addc_u32 s27, s27, 0
	s_add_i32 s28, s56, s36
	global_load_lds_dwordx4 v[190:191], off
	v_lshl_add_u64 v[190:191], s[26:27], 0, v[132:133]
	s_mov_b32 m0, s28
	s_nop 0
	global_load_lds_dwordx4 v[190:191], off
	v_lshl_add_u64 v[190:191], s[26:27], 0, v[128:129]
	s_add_i32 m0, s28, 0x2000
	s_nop 0
	global_load_lds_dwordx4 v[190:191], off
	v_lshl_add_u64 v[190:191], v[220:221], 0, s[10:11]
	s_mov_b32 m0, s42
	s_nop 0
	global_load_lds_dwordx4 v[190:191], off
	v_lshl_add_u64 v[190:191], v[222:223], 0, s[10:11]
	s_mov_b32 m0, s43
	s_nop 0
	global_load_lds_dwordx4 v[190:191], off
	s_waitcnt vmcnt(8)
	s_waitcnt lgkmcnt(0)
	s_barrier
	s_waitcnt lgkmcnt(0)
	v_mfma_f32_16x16x32_bf16 v[60:63], v[144:147], v[182:185], v[60:63]
	v_mfma_f32_16x16x32_bf16 v[56:59], v[158:161], v[182:185], v[56:59]
	v_mfma_f32_16x16x32_bf16 v[44:47], v[158:161], v[194:197], v[44:47]
	v_mfma_f32_16x16x32_bf16 v[52:55], v[144:147], v[194:197], v[52:55]
	v_mfma_f32_16x16x32_bf16 v[36:39], v[144:147], v[202:205], v[36:39]
	v_mfma_f32_16x16x32_bf16 v[28:31], v[158:161], v[202:205], v[28:31]
	v_mfma_f32_16x16x32_bf16 v[12:15], v[158:161], v[210:213], v[12:15]
	v_mfma_f32_16x16x32_bf16 v[20:23], v[144:147], v[210:213], v[20:23]
	v_mfma_f32_16x16x32_bf16 v[60:63], v[154:157], v[186:189], v[60:63]
	v_mfma_f32_16x16x32_bf16 v[56:59], v[162:165], v[186:189], v[56:59]
	v_mfma_f32_16x16x32_bf16 v[44:47], v[162:165], v[198:201], v[44:47]
	v_mfma_f32_16x16x32_bf16 v[52:55], v[154:157], v[198:201], v[52:55]
	v_mfma_f32_16x16x32_bf16 v[36:39], v[154:157], v[206:209], v[36:39]
	v_mfma_f32_16x16x32_bf16 v[28:31], v[162:165], v[206:209], v[28:31]
	v_mfma_f32_16x16x32_bf16 v[12:15], v[162:165], v[214:217], v[12:15]
	v_mfma_f32_16x16x32_bf16 v[20:23], v[154:157], v[214:217], v[20:23]
	v_mfma_f32_16x16x32_bf16 v[48:51], v[166:169], v[182:185], v[48:51]
	v_mfma_f32_16x16x32_bf16 v[40:43], v[174:177], v[182:185], v[40:43]
	v_mfma_f32_16x16x32_bf16 v[24:27], v[174:177], v[194:197], v[24:27]
	v_mfma_f32_16x16x32_bf16 v[32:35], v[166:169], v[194:197], v[32:35]
	v_mfma_f32_16x16x32_bf16 v[16:19], v[166:169], v[202:205], v[16:19]
	v_mfma_f32_16x16x32_bf16 v[8:11], v[174:177], v[202:205], v[8:11]
	v_mfma_f32_16x16x32_bf16 v[0:3], v[174:177], v[210:213], v[0:3]
	v_mfma_f32_16x16x32_bf16 v[4:7], v[166:169], v[210:213], v[4:7]
	v_mfma_f32_16x16x32_bf16 v[48:51], v[170:173], v[186:189], v[48:51]
	v_mfma_f32_16x16x32_bf16 v[40:43], v[178:181], v[186:189], v[40:43]
	v_mfma_f32_16x16x32_bf16 v[24:27], v[178:181], v[198:201], v[24:27]
	v_mfma_f32_16x16x32_bf16 v[32:35], v[170:173], v[198:201], v[32:35]
	v_mfma_f32_16x16x32_bf16 v[16:19], v[170:173], v[206:209], v[16:19]
	v_mfma_f32_16x16x32_bf16 v[8:11], v[178:181], v[206:209], v[8:11]
	v_mfma_f32_16x16x32_bf16 v[0:3], v[178:181], v[214:217], v[0:3]
	v_mfma_f32_16x16x32_bf16 v[4:7], v[170:173], v[214:217], v[4:7]
	s_barrier
	s_add_i32 s60, s60, 2
	s_add_u32 s24, s24, 0x100
	s_addc_u32 s25, s25, 0
	s_add_u32 s58, s58, 0x100
	s_addc_u32 s59, s59, 0
	s_cmp_gt_u32 s60, 29
	s_cbranch_scc0 .LBB0_226
	s_and_b64 vcc, exec, s[12:13]
	s_cbranch_vccz .LBB0_229
	s_barrier

.LBB0_589:
	ds_read_b128 v[144:147], v153
	ds_read_b128 v[158:161], v153 offset:1024
	ds_read_b128 v[162:165], v153 offset:2048
	ds_read_b128 v[166:169], v153 offset:3072
	ds_read_b128 v[170:173], v154
	ds_read_b128 v[174:177], v154 offset:1024
	ds_read_b128 v[178:181], v154 offset:2048
	ds_read_b128 v[182:185], v154 offset:3072
	s_add_u32 s33, s48, 0xfff80080
	s_addc_u32 s50, s49, -1
	s_cmp_eq_u32 s77, 28
	s_cselect_b32 s59, s35, s50
	s_cselect_b32 s58, s41, s33
	s_cselect_b32 s51, s31, s75
	s_cselect_b32 s50, s73, s74
	v_lshl_add_u64 v[148:149], s[48:49], 0, v[136:137]
	s_add_i32 m0, s43, 0xc000
	ds_read_b128 v[186:189], v155
	ds_read_b128 v[194:197], v155 offset:1024
	ds_read_b128 v[198:201], v155 offset:2048
	ds_read_b128 v[202:205], v155 offset:3072
	ds_read_b128 v[206:209], v155 offset:4096
	ds_read_b128 v[210:213], v155 offset:5120
	ds_read_b128 v[214:217], v155 offset:6144
	ds_read_b128 v[218:221], v155 offset:7168
	global_load_lds_dwordx4 v[148:149], off
	v_lshl_add_u64 v[148:149], s[48:49], 0, v[138:139]
	s_add_i32 m0, s43, 0xe000
	s_nop 0
	global_load_lds_dwordx4 v[148:149], off
	s_waitcnt vmcnt(8)
	s_waitcnt lgkmcnt(0)
	s_barrier
	s_waitcnt lgkmcnt(0)
	v_mfma_f32_16x16x32_bf16 v[124:127], v[144:147], v[186:189], v[124:127]
	v_mfma_f32_16x16x32_bf16 v[120:123], v[162:165], v[186:189], v[120:123]
	v_mfma_f32_16x16x32_bf16 v[104:107], v[162:165], v[198:201], v[104:107]
	v_mfma_f32_16x16x32_bf16 v[108:111], v[144:147], v[198:201], v[108:111]
	v_mfma_f32_16x16x32_bf16 v[92:95], v[144:147], v[206:209], v[92:95]
	v_mfma_f32_16x16x32_bf16 v[88:91], v[162:165], v[206:209], v[88:91]
	v_mfma_f32_16x16x32_bf16 v[72:75], v[162:165], v[214:217], v[72:75]
	v_mfma_f32_16x16x32_bf16 v[76:79], v[144:147], v[214:217], v[76:79]
	v_mfma_f32_16x16x32_bf16 v[124:127], v[158:161], v[194:197], v[124:127]
	v_mfma_f32_16x16x32_bf16 v[120:123], v[166:169], v[194:197], v[120:123]
	v_mfma_f32_16x16x32_bf16 v[104:107], v[166:169], v[202:205], v[104:107]
	v_mfma_f32_16x16x32_bf16 v[108:111], v[158:161], v[202:205], v[108:111]
	v_mfma_f32_16x16x32_bf16 v[92:95], v[158:161], v[210:213], v[92:95]
	v_mfma_f32_16x16x32_bf16 v[88:91], v[166:169], v[210:213], v[88:91]
	v_mfma_f32_16x16x32_bf16 v[72:75], v[166:169], v[218:221], v[72:75]
	v_mfma_f32_16x16x32_bf16 v[76:79], v[158:161], v[218:221], v[76:79]
	v_mfma_f32_16x16x32_bf16 v[116:119], v[170:173], v[186:189], v[116:119]
	v_mfma_f32_16x16x32_bf16 v[112:115], v[178:181], v[186:189], v[112:115]
	v_mfma_f32_16x16x32_bf16 v[96:99], v[178:181], v[198:201], v[96:99]
	v_mfma_f32_16x16x32_bf16 v[100:103], v[170:173], v[198:201], v[100:103]
	v_mfma_f32_16x16x32_bf16 v[84:87], v[170:173], v[206:209], v[84:87]
	v_mfma_f32_16x16x32_bf16 v[80:83], v[178:181], v[206:209], v[80:83]
	v_mfma_f32_16x16x32_bf16 v[64:67], v[178:181], v[214:217], v[64:67]
	v_mfma_f32_16x16x32_bf16 v[68:71], v[170:173], v[214:217], v[68:71]
	v_mfma_f32_16x16x32_bf16 v[116:119], v[174:177], v[194:197], v[116:119]
	v_mfma_f32_16x16x32_bf16 v[112:115], v[182:185], v[194:197], v[112:115]
	v_mfma_f32_16x16x32_bf16 v[96:99], v[182:185], v[202:205], v[96:99]
	v_mfma_f32_16x16x32_bf16 v[100:103], v[174:177], v[202:205], v[100:103]
	v_mfma_f32_16x16x32_bf16 v[84:87], v[174:177], v[210:213], v[84:87]
	v_mfma_f32_16x16x32_bf16 v[80:83], v[182:185], v[210:213], v[80:83]
	v_mfma_f32_16x16x32_bf16 v[64:67], v[182:185], v[218:221], v[64:67]
	v_mfma_f32_16x16x32_bf16 v[68:71], v[174:177], v[218:221], v[68:71]
	s_barrier
	s_add_i32 s33, s71, s64
	v_lshl_add_u64 v[148:149], s[50:51], 0, v[130:131]
	s_mov_b32 m0, s33
	ds_read_b128 v[186:189], v155 offset:16384
	ds_read_b128 v[194:197], v155 offset:17408
	ds_read_b128 v[198:201], v155 offset:18432
	ds_read_b128 v[202:205], v155 offset:19456
	ds_read_b128 v[206:209], v155 offset:20480
	ds_read_b128 v[210:213], v155 offset:21504
	ds_read_b128 v[214:217], v155 offset:22528
	ds_read_b128 v[218:221], v155 offset:23552
	global_load_lds_dwordx4 v[148:149], off
	s_add_i32 m0, s33, 0x2000
	s_add_u32 s54, s50, 0x80000
	v_lshl_add_u64 v[190:191], s[50:51], 0, v[134:135]
	s_addc_u32 s55, s51, 0
	s_add_i32 s33, s72, s64
	global_load_lds_dwordx4 v[190:191], off
	v_lshl_add_u64 v[222:223], s[54:55], 0, v[130:131]
	s_mov_b32 m0, s33
	v_lshl_add_u64 v[224:225], s[58:59], 0, v[132:133]
	global_load_lds_dwordx4 v[222:223], off
	v_lshl_add_u64 v[222:223], s[54:55], 0, v[134:135]
	s_add_i32 m0, s33, 0x2000
	s_nop 0
	global_load_lds_dwordx4 v[222:223], off
	v_lshl_add_u64 v[222:223], s[58:59], 0, v[128:129]
	s_mov_b32 m0, s43
	s_nop 0
	global_load_lds_dwordx4 v[222:223], off
	s_mov_b32 m0, s65
	s_nop 0
	global_load_lds_dwordx4 v[224:225], off
	s_waitcnt vmcnt(8)
	s_waitcnt lgkmcnt(0)
	s_barrier
	s_waitcnt lgkmcnt(0)
	v_mfma_f32_16x16x32_bf16 v[60:63], v[144:147], v[186:189], v[60:63]
	v_mfma_f32_16x16x32_bf16 v[56:59], v[162:165], v[186:189], v[56:59]
	v_mfma_f32_16x16x32_bf16 v[40:43], v[162:165], v[198:201], v[40:43]
	v_mfma_f32_16x16x32_bf16 v[44:47], v[144:147], v[198:201], v[44:47]
	v_mfma_f32_16x16x32_bf16 v[28:31], v[144:147], v[206:209], v[28:31]
	v_mfma_f32_16x16x32_bf16 v[24:27], v[162:165], v[206:209], v[24:27]
	v_mfma_f32_16x16x32_bf16 v[8:11], v[162:165], v[214:217], v[8:11]
	v_mfma_f32_16x16x32_bf16 v[12:15], v[144:147], v[214:217], v[12:15]
	v_mfma_f32_16x16x32_bf16 v[60:63], v[158:161], v[194:197], v[60:63]
	v_mfma_f32_16x16x32_bf16 v[56:59], v[166:169], v[194:197], v[56:59]
	v_mfma_f32_16x16x32_bf16 v[40:43], v[166:169], v[202:205], v[40:43]
	v_mfma_f32_16x16x32_bf16 v[44:47], v[158:161], v[202:205], v[44:47]
	v_mfma_f32_16x16x32_bf16 v[28:31], v[158:161], v[210:213], v[28:31]
	v_mfma_f32_16x16x32_bf16 v[24:27], v[166:169], v[210:213], v[24:27]
	v_mfma_f32_16x16x32_bf16 v[8:11], v[166:169], v[218:221], v[8:11]
	v_mfma_f32_16x16x32_bf16 v[12:15], v[158:161], v[218:221], v[12:15]
	v_mfma_f32_16x16x32_bf16 v[52:55], v[170:173], v[186:189], v[52:55]
	v_mfma_f32_16x16x32_bf16 v[48:51], v[178:181], v[186:189], v[48:51]
	v_mfma_f32_16x16x32_bf16 v[32:35], v[178:181], v[198:201], v[32:35]
	v_mfma_f32_16x16x32_bf16 v[36:39], v[170:173], v[198:201], v[36:39]
	v_mfma_f32_16x16x32_bf16 v[20:23], v[170:173], v[206:209], v[20:23]
	v_mfma_f32_16x16x32_bf16 v[16:19], v[178:181], v[206:209], v[16:19]
	v_mfma_f32_16x16x32_bf16 v[0:3], v[178:181], v[214:217], v[0:3]
	v_mfma_f32_16x16x32_bf16 v[4:7], v[170:173], v[214:217], v[4:7]
	v_mfma_f32_16x16x32_bf16 v[52:55], v[174:177], v[194:197], v[52:55]
	v_mfma_f32_16x16x32_bf16 v[48:51], v[182:185], v[194:197], v[48:51]
	v_mfma_f32_16x16x32_bf16 v[32:35], v[182:185], v[202:205], v[32:35]
	v_mfma_f32_16x16x32_bf16 v[36:39], v[174:177], v[202:205], v[36:39]
	v_mfma_f32_16x16x32_bf16 v[20:23], v[174:177], v[210:213], v[20:23]
	v_mfma_f32_16x16x32_bf16 v[16:19], v[182:185], v[210:213], v[16:19]
	v_mfma_f32_16x16x32_bf16 v[0:3], v[182:185], v[218:221], v[0:3]
	v_mfma_f32_16x16x32_bf16 v[4:7], v[174:177], v[218:221], v[4:7]
	s_barrier
	s_add_i32 s33, 0, 0x18000
	v_add_u32_e32 v157, s33, v151
	s_add_i32 s56, 0, 0x1c000
	ds_read_b128 v[144:147], v157
	ds_read_b128 v[158:161], v157 offset:1024
	ds_read_b128 v[162:165], v157 offset:2048
	ds_read_b128 v[166:169], v157 offset:3072
	v_add_u32_e32 v157, s56, v151
	ds_read_b128 v[170:173], v157
	ds_read_b128 v[174:177], v157 offset:1024
	ds_read_b128 v[178:181], v157 offset:2048
	ds_read_b128 v[182:185], v157 offset:3072
	s_add_u32 s54, s58, 0x80000
	s_addc_u32 s55, s59, 0
	s_mov_b32 m0, s66
	v_lshl_add_u64 v[226:227], s[54:55], 0, v[128:129]
	ds_read_b128 v[186:189], v155 offset:32768
	ds_read_b128 v[194:197], v155 offset:33792
	ds_read_b128 v[198:201], v155 offset:34816
	ds_read_b128 v[202:205], v155 offset:35840
	ds_read_b128 v[206:209], v155 offset:36864
	ds_read_b128 v[210:213], v155 offset:37888
	ds_read_b128 v[214:217], v155 offset:38912
	ds_read_b128 v[218:221], v155 offset:39936
	global_load_lds_dwordx4 v[226:227], off
	v_lshl_add_u64 v[226:227], s[54:55], 0, v[132:133]
	s_mov_b32 m0, s67
	s_nop 0
	global_load_lds_dwordx4 v[226:227], off
	s_waitcnt vmcnt(8)
	s_waitcnt lgkmcnt(0)
	s_barrier
	s_waitcnt lgkmcnt(0)
	v_mfma_f32_16x16x32_bf16 v[124:127], v[144:147], v[186:189], v[124:127]
	v_mfma_f32_16x16x32_bf16 v[120:123], v[162:165], v[186:189], v[120:123]
	v_mfma_f32_16x16x32_bf16 v[104:107], v[162:165], v[198:201], v[104:107]
	v_mfma_f32_16x16x32_bf16 v[108:111], v[144:147], v[198:201], v[108:111]
	v_mfma_f32_16x16x32_bf16 v[92:95], v[144:147], v[206:209], v[92:95]
	v_mfma_f32_16x16x32_bf16 v[88:91], v[162:165], v[206:209], v[88:91]
	v_mfma_f32_16x16x32_bf16 v[72:75], v[162:165], v[214:217], v[72:75]
	v_mfma_f32_16x16x32_bf16 v[76:79], v[144:147], v[214:217], v[76:79]
	v_mfma_f32_16x16x32_bf16 v[124:127], v[158:161], v[194:197], v[124:127]
	v_mfma_f32_16x16x32_bf16 v[120:123], v[166:169], v[194:197], v[120:123]
	v_mfma_f32_16x16x32_bf16 v[104:107], v[166:169], v[202:205], v[104:107]
	v_mfma_f32_16x16x32_bf16 v[108:111], v[158:161], v[202:205], v[108:111]
	v_mfma_f32_16x16x32_bf16 v[92:95], v[158:161], v[210:213], v[92:95]
	v_mfma_f32_16x16x32_bf16 v[88:91], v[166:169], v[210:213], v[88:91]
	v_mfma_f32_16x16x32_bf16 v[72:75], v[166:169], v[218:221], v[72:75]
	v_mfma_f32_16x16x32_bf16 v[76:79], v[158:161], v[218:221], v[76:79]
	v_mfma_f32_16x16x32_bf16 v[116:119], v[170:173], v[186:189], v[116:119]
	v_mfma_f32_16x16x32_bf16 v[112:115], v[178:181], v[186:189], v[112:115]
	v_mfma_f32_16x16x32_bf16 v[96:99], v[178:181], v[198:201], v[96:99]
	v_mfma_f32_16x16x32_bf16 v[100:103], v[170:173], v[198:201], v[100:103]
	v_mfma_f32_16x16x32_bf16 v[84:87], v[170:173], v[206:209], v[84:87]
	v_mfma_f32_16x16x32_bf16 v[80:83], v[178:181], v[206:209], v[80:83]
	v_mfma_f32_16x16x32_bf16 v[64:67], v[178:181], v[214:217], v[64:67]
	v_mfma_f32_16x16x32_bf16 v[68:71], v[170:173], v[214:217], v[68:71]
	v_mfma_f32_16x16x32_bf16 v[116:119], v[174:177], v[194:197], v[116:119]
	v_mfma_f32_16x16x32_bf16 v[112:115], v[182:185], v[194:197], v[112:115]
	v_mfma_f32_16x16x32_bf16 v[96:99], v[182:185], v[202:205], v[96:99]
	v_mfma_f32_16x16x32_bf16 v[100:103], v[174:177], v[202:205], v[100:103]
	v_mfma_f32_16x16x32_bf16 v[84:87], v[174:177], v[210:213], v[84:87]
	v_mfma_f32_16x16x32_bf16 v[80:83], v[182:185], v[210:213], v[80:83]
	v_mfma_f32_16x16x32_bf16 v[64:67], v[182:185], v[218:221], v[64:67]
	v_mfma_f32_16x16x32_bf16 v[68:71], v[174:177], v[218:221], v[68:71]
	s_barrier
	s_add_i32 s33, s33, s64
	v_lshl_add_u64 v[148:149], v[148:149], 0, s[18:19]
	s_mov_b32 m0, s33
	ds_read_b128 v[186:189], v155 offset:49152
	ds_read_b128 v[194:197], v155 offset:50176
	ds_read_b128 v[198:201], v155 offset:51200
	ds_read_b128 v[202:205], v155 offset:52224
	ds_read_b128 v[206:209], v155 offset:53248
	ds_read_b128 v[210:213], v155 offset:54272
	ds_read_b128 v[214:217], v155 offset:55296
	ds_read_b128 v[218:221], v155 offset:56320
	global_load_lds_dwordx4 v[148:149], off
	s_add_i32 m0, s33, 0x2000
	s_add_u32 s50, s50, 0x80080
	v_lshl_add_u64 v[148:149], v[190:191], 0, s[18:19]
	s_addc_u32 s51, s51, 0
	s_add_i32 s33, s56, s64
	global_load_lds_dwordx4 v[148:149], off
	v_lshl_add_u64 v[148:149], s[50:51], 0, v[130:131]
	s_mov_b32 m0, s33
	s_nop 0
	global_load_lds_dwordx4 v[148:149], off
	v_lshl_add_u64 v[148:149], s[50:51], 0, v[134:135]
	s_add_i32 m0, s33, 0x2000
	s_nop 0
	global_load_lds_dwordx4 v[148:149], off
	v_lshl_add_u64 v[148:149], v[222:223], 0, s[18:19]
	s_mov_b32 m0, s69
	s_nop 0
	global_load_lds_dwordx4 v[148:149], off
	v_lshl_add_u64 v[148:149], v[224:225], 0, s[18:19]
	s_mov_b32 m0, s70
	s_nop 0
	global_load_lds_dwordx4 v[148:149], off
	s_waitcnt vmcnt(8)
	s_waitcnt lgkmcnt(0)
	s_barrier
	s_waitcnt lgkmcnt(0)
	v_mfma_f32_16x16x32_bf16 v[60:63], v[144:147], v[186:189], v[60:63]
	v_mfma_f32_16x16x32_bf16 v[56:59], v[162:165], v[186:189], v[56:59]
	v_mfma_f32_16x16x32_bf16 v[40:43], v[162:165], v[198:201], v[40:43]
	v_mfma_f32_16x16x32_bf16 v[44:47], v[144:147], v[198:201], v[44:47]
	v_mfma_f32_16x16x32_bf16 v[28:31], v[144:147], v[206:209], v[28:31]
	v_mfma_f32_16x16x32_bf16 v[24:27], v[162:165], v[206:209], v[24:27]
	v_mfma_f32_16x16x32_bf16 v[8:11], v[162:165], v[214:217], v[8:11]
	v_mfma_f32_16x16x32_bf16 v[12:15], v[144:147], v[214:217], v[12:15]
	v_mfma_f32_16x16x32_bf16 v[60:63], v[158:161], v[194:197], v[60:63]
	v_mfma_f32_16x16x32_bf16 v[56:59], v[166:169], v[194:197], v[56:59]
	v_mfma_f32_16x16x32_bf16 v[40:43], v[166:169], v[202:205], v[40:43]
	v_mfma_f32_16x16x32_bf16 v[44:47], v[158:161], v[202:205], v[44:47]
	v_mfma_f32_16x16x32_bf16 v[28:31], v[158:161], v[210:213], v[28:31]
	v_mfma_f32_16x16x32_bf16 v[24:27], v[166:169], v[210:213], v[24:27]
	v_mfma_f32_16x16x32_bf16 v[8:11], v[166:169], v[218:221], v[8:11]
	v_mfma_f32_16x16x32_bf16 v[12:15], v[158:161], v[218:221], v[12:15]
	v_mfma_f32_16x16x32_bf16 v[52:55], v[170:173], v[186:189], v[52:55]
	v_mfma_f32_16x16x32_bf16 v[48:51], v[178:181], v[186:189], v[48:51]
	v_mfma_f32_16x16x32_bf16 v[32:35], v[178:181], v[198:201], v[32:35]
	v_mfma_f32_16x16x32_bf16 v[36:39], v[170:173], v[198:201], v[36:39]
	v_mfma_f32_16x16x32_bf16 v[20:23], v[170:173], v[206:209], v[20:23]
	v_mfma_f32_16x16x32_bf16 v[16:19], v[178:181], v[206:209], v[16:19]
	v_mfma_f32_16x16x32_bf16 v[0:3], v[178:181], v[214:217], v[0:3]
	v_mfma_f32_16x16x32_bf16 v[4:7], v[170:173], v[214:217], v[4:7]
	v_mfma_f32_16x16x32_bf16 v[52:55], v[174:177], v[194:197], v[52:55]
	v_mfma_f32_16x16x32_bf16 v[48:51], v[182:185], v[194:197], v[48:51]
	v_mfma_f32_16x16x32_bf16 v[32:35], v[182:185], v[202:205], v[32:35]
	v_mfma_f32_16x16x32_bf16 v[36:39], v[174:177], v[202:205], v[36:39]
	v_mfma_f32_16x16x32_bf16 v[20:23], v[174:177], v[210:213], v[20:23]
	v_mfma_f32_16x16x32_bf16 v[16:19], v[182:185], v[210:213], v[16:19]
	v_mfma_f32_16x16x32_bf16 v[0:3], v[182:185], v[218:221], v[0:3]
	v_mfma_f32_16x16x32_bf16 v[4:7], v[174:177], v[218:221], v[4:7]
	s_barrier
	s_add_i32 s77, s77, 2
	s_add_u32 s48, s48, 0x100
	s_addc_u32 s49, s49, 0
	s_add_u32 s74, s74, 0x100
	s_addc_u32 s75, s75, 0
	s_cmp_gt_u32 s77, 29
	s_cbranch_scc0 .LBB0_589
	s_and_b64 vcc, exec, s[20:21]
	s_cbranch_vccz .LBB0_592
	s_barrier

.LBB0_673:
	ds_read_b128 v[144:147], v153
	ds_read_b128 v[158:161], v153 offset:1024
	ds_read_b128 v[162:165], v153 offset:2048
	ds_read_b128 v[166:169], v153 offset:3072
	ds_read_b128 v[170:173], v154
	ds_read_b128 v[174:177], v154 offset:1024
	ds_read_b128 v[178:181], v154 offset:2048
	ds_read_b128 v[182:185], v154 offset:3072
	s_add_u32 s33, s30, 0xfff80080
	s_addc_u32 s34, s31, -1
	s_cmp_eq_u32 s69, 28
	s_cselect_b32 s37, s25, s34
	s_cselect_b32 s36, s65, s33
	s_cselect_b32 s35, s23, s68
	s_cselect_b32 s34, s66, s67
	v_lshl_add_u64 v[148:149], s[30:31], 0, v[136:137]
	s_add_i32 m0, s48, 0xc000
	ds_read_b128 v[186:189], v155
	ds_read_b128 v[194:197], v155 offset:1024
	ds_read_b128 v[198:201], v155 offset:2048
	ds_read_b128 v[202:205], v155 offset:3072
	ds_read_b128 v[206:209], v155 offset:4096
	ds_read_b128 v[210:213], v155 offset:5120
	ds_read_b128 v[214:217], v155 offset:6144
	ds_read_b128 v[218:221], v155 offset:7168
	global_load_lds_dwordx4 v[148:149], off
	v_lshl_add_u64 v[148:149], s[30:31], 0, v[138:139]
	s_add_i32 m0, s48, 0xe000
	s_nop 0
	global_load_lds_dwordx4 v[148:149], off
	s_waitcnt vmcnt(8)
	s_waitcnt lgkmcnt(0)
	s_barrier
	s_waitcnt lgkmcnt(0)
	v_mfma_f32_16x16x32_bf16 v[116:119], v[144:147], v[186:189], v[116:119]
	v_mfma_f32_16x16x32_bf16 v[112:115], v[162:165], v[186:189], v[112:115]
	v_mfma_f32_16x16x32_bf16 v[96:99], v[162:165], v[198:201], v[96:99]
	v_mfma_f32_16x16x32_bf16 v[100:103], v[144:147], v[198:201], v[100:103]
	v_mfma_f32_16x16x32_bf16 v[84:87], v[144:147], v[206:209], v[84:87]
	v_mfma_f32_16x16x32_bf16 v[80:83], v[162:165], v[206:209], v[80:83]
	v_mfma_f32_16x16x32_bf16 v[64:67], v[162:165], v[214:217], v[64:67]
	v_mfma_f32_16x16x32_bf16 v[68:71], v[144:147], v[214:217], v[68:71]
	v_mfma_f32_16x16x32_bf16 v[116:119], v[158:161], v[194:197], v[116:119]
	v_mfma_f32_16x16x32_bf16 v[112:115], v[166:169], v[194:197], v[112:115]
	v_mfma_f32_16x16x32_bf16 v[96:99], v[166:169], v[202:205], v[96:99]
	v_mfma_f32_16x16x32_bf16 v[100:103], v[158:161], v[202:205], v[100:103]
	v_mfma_f32_16x16x32_bf16 v[84:87], v[158:161], v[210:213], v[84:87]
	v_mfma_f32_16x16x32_bf16 v[80:83], v[166:169], v[210:213], v[80:83]
	v_mfma_f32_16x16x32_bf16 v[64:67], v[166:169], v[218:221], v[64:67]
	v_mfma_f32_16x16x32_bf16 v[68:71], v[158:161], v[218:221], v[68:71]
	v_mfma_f32_16x16x32_bf16 v[124:127], v[170:173], v[186:189], v[124:127]
	v_mfma_f32_16x16x32_bf16 v[120:123], v[178:181], v[186:189], v[120:123]
	v_mfma_f32_16x16x32_bf16 v[104:107], v[178:181], v[198:201], v[104:107]
	v_mfma_f32_16x16x32_bf16 v[108:111], v[170:173], v[198:201], v[108:111]
	v_mfma_f32_16x16x32_bf16 v[92:95], v[170:173], v[206:209], v[92:95]
	v_mfma_f32_16x16x32_bf16 v[88:91], v[178:181], v[206:209], v[88:91]
	v_mfma_f32_16x16x32_bf16 v[72:75], v[178:181], v[214:217], v[72:75]
	v_mfma_f32_16x16x32_bf16 v[76:79], v[170:173], v[214:217], v[76:79]
	v_mfma_f32_16x16x32_bf16 v[124:127], v[174:177], v[194:197], v[124:127]
	v_mfma_f32_16x16x32_bf16 v[120:123], v[182:185], v[194:197], v[120:123]
	v_mfma_f32_16x16x32_bf16 v[104:107], v[182:185], v[202:205], v[104:107]
	v_mfma_f32_16x16x32_bf16 v[108:111], v[174:177], v[202:205], v[108:111]
	v_mfma_f32_16x16x32_bf16 v[92:95], v[174:177], v[210:213], v[92:95]
	v_mfma_f32_16x16x32_bf16 v[88:91], v[182:185], v[210:213], v[88:91]
	v_mfma_f32_16x16x32_bf16 v[72:75], v[182:185], v[218:221], v[72:75]
	v_mfma_f32_16x16x32_bf16 v[76:79], v[174:177], v[218:221], v[76:79]
	s_barrier
	s_add_i32 s33, s61, s42
	v_lshl_add_u64 v[148:149], s[34:35], 0, v[132:133]
	s_mov_b32 m0, s33
	ds_read_b128 v[186:189], v155 offset:16384
	ds_read_b128 v[194:197], v155 offset:17408
	ds_read_b128 v[198:201], v155 offset:18432
	ds_read_b128 v[202:205], v155 offset:19456
	ds_read_b128 v[206:209], v155 offset:20480
	ds_read_b128 v[210:213], v155 offset:21504
	ds_read_b128 v[214:217], v155 offset:22528
	ds_read_b128 v[218:221], v155 offset:23552
	global_load_lds_dwordx4 v[148:149], off
	s_add_i32 m0, s33, 0x2000
	s_add_u32 s54, s34, 0x80000
	v_lshl_add_u64 v[190:191], s[34:35], 0, v[128:129]
	s_addc_u32 s55, s35, 0
	s_add_i32 s33, s62, s42
	global_load_lds_dwordx4 v[190:191], off
	v_lshl_add_u64 v[222:223], s[54:55], 0, v[132:133]
	s_mov_b32 m0, s33
	v_lshl_add_u64 v[224:225], s[36:37], 0, v[130:131]
	global_load_lds_dwordx4 v[222:223], off
	v_lshl_add_u64 v[222:223], s[54:55], 0, v[128:129]
	s_add_i32 m0, s33, 0x2000
	s_nop 0
	global_load_lds_dwordx4 v[222:223], off
	v_lshl_add_u64 v[222:223], s[36:37], 0, v[134:135]
	s_mov_b32 m0, s48
	s_nop 0
	global_load_lds_dwordx4 v[222:223], off
	s_mov_b32 m0, s49
	s_nop 0
	global_load_lds_dwordx4 v[224:225], off
	s_waitcnt vmcnt(8)
	s_waitcnt lgkmcnt(0)
	s_barrier
	s_waitcnt lgkmcnt(0)
	v_mfma_f32_16x16x32_bf16 v[52:55], v[144:147], v[186:189], v[52:55]
	v_mfma_f32_16x16x32_bf16 v[48:51], v[162:165], v[186:189], v[48:51]
	v_mfma_f32_16x16x32_bf16 v[32:35], v[162:165], v[198:201], v[32:35]
	v_mfma_f32_16x16x32_bf16 v[36:39], v[144:147], v[198:201], v[36:39]
	v_mfma_f32_16x16x32_bf16 v[20:23], v[144:147], v[206:209], v[20:23]
	v_mfma_f32_16x16x32_bf16 v[16:19], v[162:165], v[206:209], v[16:19]
	v_mfma_f32_16x16x32_bf16 v[0:3], v[162:165], v[214:217], v[0:3]
	v_mfma_f32_16x16x32_bf16 v[4:7], v[144:147], v[214:217], v[4:7]
	v_mfma_f32_16x16x32_bf16 v[52:55], v[158:161], v[194:197], v[52:55]
	v_mfma_f32_16x16x32_bf16 v[48:51], v[166:169], v[194:197], v[48:51]
	v_mfma_f32_16x16x32_bf16 v[32:35], v[166:169], v[202:205], v[32:35]
	v_mfma_f32_16x16x32_bf16 v[36:39], v[158:161], v[202:205], v[36:39]
	v_mfma_f32_16x16x32_bf16 v[20:23], v[158:161], v[210:213], v[20:23]
	v_mfma_f32_16x16x32_bf16 v[16:19], v[166:169], v[210:213], v[16:19]
	v_mfma_f32_16x16x32_bf16 v[0:3], v[166:169], v[218:221], v[0:3]
	v_mfma_f32_16x16x32_bf16 v[4:7], v[158:161], v[218:221], v[4:7]
	v_mfma_f32_16x16x32_bf16 v[60:63], v[170:173], v[186:189], v[60:63]
	v_mfma_f32_16x16x32_bf16 v[56:59], v[178:181], v[186:189], v[56:59]
	v_mfma_f32_16x16x32_bf16 v[40:43], v[178:181], v[198:201], v[40:43]
	v_mfma_f32_16x16x32_bf16 v[44:47], v[170:173], v[198:201], v[44:47]
	v_mfma_f32_16x16x32_bf16 v[28:31], v[170:173], v[206:209], v[28:31]
	v_mfma_f32_16x16x32_bf16 v[24:27], v[178:181], v[206:209], v[24:27]
	v_mfma_f32_16x16x32_bf16 v[8:11], v[178:181], v[214:217], v[8:11]
	v_mfma_f32_16x16x32_bf16 v[12:15], v[170:173], v[214:217], v[12:15]
	v_mfma_f32_16x16x32_bf16 v[60:63], v[174:177], v[194:197], v[60:63]
	v_mfma_f32_16x16x32_bf16 v[56:59], v[182:185], v[194:197], v[56:59]
	v_mfma_f32_16x16x32_bf16 v[40:43], v[182:185], v[202:205], v[40:43]
	v_mfma_f32_16x16x32_bf16 v[44:47], v[174:177], v[202:205], v[44:47]
	v_mfma_f32_16x16x32_bf16 v[28:31], v[174:177], v[210:213], v[28:31]
	v_mfma_f32_16x16x32_bf16 v[24:27], v[182:185], v[210:213], v[24:27]
	v_mfma_f32_16x16x32_bf16 v[8:11], v[182:185], v[218:221], v[8:11]
	v_mfma_f32_16x16x32_bf16 v[12:15], v[174:177], v[218:221], v[12:15]
	s_barrier
	s_add_i32 s33, 0, 0x18000
	s_add_i32 s54, 0, 0x1c000
	v_add_u32_e32 v166, s33, v151
	v_add_u32_e32 v182, s54, v151
	ds_read_b128 v[144:147], v166
	ds_read_b128 v[158:161], v166 offset:1024
	ds_read_b128 v[162:165], v166 offset:2048
	ds_read_b128 v[166:169], v166 offset:3072
	ds_read_b128 v[170:173], v182
	ds_read_b128 v[174:177], v182 offset:1024
	ds_read_b128 v[178:181], v182 offset:2048
	ds_read_b128 v[182:185], v182 offset:3072
	s_add_u32 s36, s36, 0x80000
	s_addc_u32 s37, s37, 0
	s_mov_b32 m0, s50
	v_lshl_add_u64 v[226:227], s[36:37], 0, v[134:135]
	ds_read_b128 v[186:189], v155 offset:32768
	ds_read_b128 v[194:197], v155 offset:33792
	ds_read_b128 v[198:201], v155 offset:34816
	ds_read_b128 v[202:205], v155 offset:35840
	ds_read_b128 v[206:209], v155 offset:36864
	ds_read_b128 v[210:213], v155 offset:37888
	ds_read_b128 v[214:217], v155 offset:38912
	ds_read_b128 v[218:221], v155 offset:39936
	global_load_lds_dwordx4 v[226:227], off
	v_lshl_add_u64 v[226:227], s[36:37], 0, v[130:131]
	s_mov_b32 m0, s51
	s_nop 0
	global_load_lds_dwordx4 v[226:227], off
	s_waitcnt vmcnt(8)
	s_waitcnt lgkmcnt(0)
	s_barrier
	s_waitcnt lgkmcnt(0)
	v_mfma_f32_16x16x32_bf16 v[116:119], v[144:147], v[186:189], v[116:119]
	v_mfma_f32_16x16x32_bf16 v[112:115], v[162:165], v[186:189], v[112:115]
	v_mfma_f32_16x16x32_bf16 v[96:99], v[162:165], v[198:201], v[96:99]
	v_mfma_f32_16x16x32_bf16 v[100:103], v[144:147], v[198:201], v[100:103]
	v_mfma_f32_16x16x32_bf16 v[84:87], v[144:147], v[206:209], v[84:87]
	v_mfma_f32_16x16x32_bf16 v[80:83], v[162:165], v[206:209], v[80:83]
	v_mfma_f32_16x16x32_bf16 v[64:67], v[162:165], v[214:217], v[64:67]
	v_mfma_f32_16x16x32_bf16 v[68:71], v[144:147], v[214:217], v[68:71]
	v_mfma_f32_16x16x32_bf16 v[116:119], v[158:161], v[194:197], v[116:119]
	v_mfma_f32_16x16x32_bf16 v[112:115], v[166:169], v[194:197], v[112:115]
	v_mfma_f32_16x16x32_bf16 v[96:99], v[166:169], v[202:205], v[96:99]
	v_mfma_f32_16x16x32_bf16 v[100:103], v[158:161], v[202:205], v[100:103]
	v_mfma_f32_16x16x32_bf16 v[84:87], v[158:161], v[210:213], v[84:87]
	v_mfma_f32_16x16x32_bf16 v[80:83], v[166:169], v[210:213], v[80:83]
	v_mfma_f32_16x16x32_bf16 v[64:67], v[166:169], v[218:221], v[64:67]
	v_mfma_f32_16x16x32_bf16 v[68:71], v[158:161], v[218:221], v[68:71]
	v_mfma_f32_16x16x32_bf16 v[124:127], v[170:173], v[186:189], v[124:127]
	v_mfma_f32_16x16x32_bf16 v[120:123], v[178:181], v[186:189], v[120:123]
	v_mfma_f32_16x16x32_bf16 v[104:107], v[178:181], v[198:201], v[104:107]
	v_mfma_f32_16x16x32_bf16 v[108:111], v[170:173], v[198:201], v[108:111]
	v_mfma_f32_16x16x32_bf16 v[92:95], v[170:173], v[206:209], v[92:95]
	v_mfma_f32_16x16x32_bf16 v[88:91], v[178:181], v[206:209], v[88:91]
	v_mfma_f32_16x16x32_bf16 v[72:75], v[178:181], v[214:217], v[72:75]
	v_mfma_f32_16x16x32_bf16 v[76:79], v[170:173], v[214:217], v[76:79]
	v_mfma_f32_16x16x32_bf16 v[124:127], v[174:177], v[194:197], v[124:127]
	v_mfma_f32_16x16x32_bf16 v[120:123], v[182:185], v[194:197], v[120:123]
	v_mfma_f32_16x16x32_bf16 v[104:107], v[182:185], v[202:205], v[104:107]
	v_mfma_f32_16x16x32_bf16 v[108:111], v[174:177], v[202:205], v[108:111]
	v_mfma_f32_16x16x32_bf16 v[92:95], v[174:177], v[210:213], v[92:95]
	v_mfma_f32_16x16x32_bf16 v[88:91], v[182:185], v[210:213], v[88:91]
	v_mfma_f32_16x16x32_bf16 v[72:75], v[182:185], v[218:221], v[72:75]
	v_mfma_f32_16x16x32_bf16 v[76:79], v[174:177], v[218:221], v[76:79]
	s_barrier
	s_add_i32 s33, s33, s42
	v_lshl_add_u64 v[148:149], v[148:149], 0, s[18:19]
	s_mov_b32 m0, s33
	ds_read_b128 v[186:189], v155 offset:49152
	ds_read_b128 v[194:197], v155 offset:50176
	ds_read_b128 v[198:201], v155 offset:51200
	ds_read_b128 v[202:205], v155 offset:52224
	ds_read_b128 v[206:209], v155 offset:53248
	ds_read_b128 v[210:213], v155 offset:54272
	ds_read_b128 v[214:217], v155 offset:55296
	ds_read_b128 v[218:221], v155 offset:56320
	global_load_lds_dwordx4 v[148:149], off
	s_add_i32 m0, s33, 0x2000
	s_add_u32 s34, s34, 0x80080
	v_lshl_add_u64 v[148:149], v[190:191], 0, s[18:19]
	s_addc_u32 s35, s35, 0
	s_add_i32 s33, s54, s42
	global_load_lds_dwordx4 v[148:149], off
	v_lshl_add_u64 v[148:149], s[34:35], 0, v[132:133]
	s_mov_b32 m0, s33
	s_nop 0
	global_load_lds_dwordx4 v[148:149], off
	v_lshl_add_u64 v[148:149], s[34:35], 0, v[128:129]
	s_add_i32 m0, s33, 0x2000
	s_nop 0
	global_load_lds_dwordx4 v[148:149], off
	v_lshl_add_u64 v[148:149], v[222:223], 0, s[18:19]
	s_mov_b32 m0, s59
	s_nop 0
	global_load_lds_dwordx4 v[148:149], off
	v_lshl_add_u64 v[148:149], v[224:225], 0, s[18:19]
	s_mov_b32 m0, s60
	s_nop 0
	global_load_lds_dwordx4 v[148:149], off
	s_waitcnt vmcnt(8)
	s_waitcnt lgkmcnt(0)
	s_barrier
	s_waitcnt lgkmcnt(0)
	v_mfma_f32_16x16x32_bf16 v[52:55], v[144:147], v[186:189], v[52:55]
	v_mfma_f32_16x16x32_bf16 v[48:51], v[162:165], v[186:189], v[48:51]
	v_mfma_f32_16x16x32_bf16 v[32:35], v[162:165], v[198:201], v[32:35]
	v_mfma_f32_16x16x32_bf16 v[36:39], v[144:147], v[198:201], v[36:39]
	v_mfma_f32_16x16x32_bf16 v[20:23], v[144:147], v[206:209], v[20:23]
	v_mfma_f32_16x16x32_bf16 v[16:19], v[162:165], v[206:209], v[16:19]
	v_mfma_f32_16x16x32_bf16 v[0:3], v[162:165], v[214:217], v[0:3]
	v_mfma_f32_16x16x32_bf16 v[4:7], v[144:147], v[214:217], v[4:7]
	v_mfma_f32_16x16x32_bf16 v[52:55], v[158:161], v[194:197], v[52:55]
	v_mfma_f32_16x16x32_bf16 v[48:51], v[166:169], v[194:197], v[48:51]
	v_mfma_f32_16x16x32_bf16 v[32:35], v[166:169], v[202:205], v[32:35]
	v_mfma_f32_16x16x32_bf16 v[36:39], v[158:161], v[202:205], v[36:39]
	v_mfma_f32_16x16x32_bf16 v[20:23], v[158:161], v[210:213], v[20:23]
	v_mfma_f32_16x16x32_bf16 v[16:19], v[166:169], v[210:213], v[16:19]
	v_mfma_f32_16x16x32_bf16 v[0:3], v[166:169], v[218:221], v[0:3]
	v_mfma_f32_16x16x32_bf16 v[4:7], v[158:161], v[218:221], v[4:7]
	v_mfma_f32_16x16x32_bf16 v[60:63], v[170:173], v[186:189], v[60:63]
	v_mfma_f32_16x16x32_bf16 v[56:59], v[178:181], v[186:189], v[56:59]
	v_mfma_f32_16x16x32_bf16 v[40:43], v[178:181], v[198:201], v[40:43]
	v_mfma_f32_16x16x32_bf16 v[44:47], v[170:173], v[198:201], v[44:47]
	v_mfma_f32_16x16x32_bf16 v[28:31], v[170:173], v[206:209], v[28:31]
	v_mfma_f32_16x16x32_bf16 v[24:27], v[178:181], v[206:209], v[24:27]
	v_mfma_f32_16x16x32_bf16 v[8:11], v[178:181], v[214:217], v[8:11]
	v_mfma_f32_16x16x32_bf16 v[12:15], v[170:173], v[214:217], v[12:15]
	v_mfma_f32_16x16x32_bf16 v[60:63], v[174:177], v[194:197], v[60:63]
	v_mfma_f32_16x16x32_bf16 v[56:59], v[182:185], v[194:197], v[56:59]
	v_mfma_f32_16x16x32_bf16 v[40:43], v[182:185], v[202:205], v[40:43]
	v_mfma_f32_16x16x32_bf16 v[44:47], v[174:177], v[202:205], v[44:47]
	v_mfma_f32_16x16x32_bf16 v[28:31], v[174:177], v[210:213], v[28:31]
	v_mfma_f32_16x16x32_bf16 v[24:27], v[182:185], v[210:213], v[24:27]
	v_mfma_f32_16x16x32_bf16 v[8:11], v[182:185], v[218:221], v[8:11]
	v_mfma_f32_16x16x32_bf16 v[12:15], v[174:177], v[218:221], v[12:15]
	s_barrier
	s_add_i32 s69, s69, 2
	s_add_u32 s30, s30, 0x100
	s_addc_u32 s31, s31, 0
	s_add_u32 s67, s67, 0x100
	s_addc_u32 s68, s68, 0
	s_cmp_gt_u32 s69, 29
	s_cbranch_scc0 .LBB0_673
	v_lshl_add_u32 v144, s8, 8, v150
	v_ashrrev_i32_e32 v145, 31, v144
	v_lshl_add_u64 v[148:149], v[144:145], 2, s[16:17]
	global_load_dword v172, v[148:149], off
	global_load_dword v173, v[148:149], off offset:64
	global_load_dword v174, v[148:149], off offset:128
	global_load_dword v175, v[148:149], off offset:192
	global_load_dword v176, v[148:149], off offset:512
	global_load_dword v177, v[148:149], off offset:576
	global_load_dword v178, v[148:149], off offset:640
	global_load_dword v179, v[148:149], off offset:704
	s_and_b64 vcc, exec, s[20:21]
	s_cbranch_vccz .LBB0_676
	s_barrier

.LBB0_1187:
	ds_read_b128 v[152:155], v161
	ds_read_b128 v[166:169], v161 offset:1024
	ds_read_b128 v[170:173], v161 offset:2048
	ds_read_b128 v[174:177], v161 offset:3072
	ds_read_b128 v[178:181], v162
	ds_read_b128 v[182:185], v162 offset:1024
	ds_read_b128 v[186:189], v162 offset:2048
	ds_read_b128 v[194:197], v162 offset:3072
	s_add_u32 s30, s28, 0x100
	s_addc_u32 s31, s29, 0
	s_cmpk_eq_i32 s68, 0x54
	s_cselect_b32 s37, s11, s31
	s_cselect_b32 s36, s10, s30
	s_cselect_b32 s35, s27, s67
	s_cselect_b32 s34, s26, s66
	v_lshl_add_u64 v[156:157], s[28:29], 0, v[136:137]
	s_add_i32 m0, s43, 0xc000
	ds_read_b128 v[198:201], v163
	ds_read_b128 v[202:205], v163 offset:1024
	ds_read_b128 v[206:209], v163 offset:2048
	ds_read_b128 v[210:213], v163 offset:3072
	ds_read_b128 v[214:217], v163 offset:4096
	ds_read_b128 v[218:221], v163 offset:5120
	ds_read_b128 v[222:225], v163 offset:6144
	ds_read_b128 v[226:229], v163 offset:7168
	global_load_lds_dwordx4 v[156:157], off
	v_lshl_add_u64 v[156:157], s[28:29], 0, v[138:139]
	s_add_i32 m0, s43, 0xe000
	s_nop 0
	global_load_lds_dwordx4 v[156:157], off
	s_waitcnt vmcnt(8)
	s_waitcnt lgkmcnt(0)
	s_barrier
	s_waitcnt lgkmcnt(0)
	v_mfma_f32_16x16x32_bf16 v[124:127], v[152:155], v[198:201], v[124:127]
	v_mfma_f32_16x16x32_bf16 v[120:123], v[170:173], v[198:201], v[120:123]
	v_mfma_f32_16x16x32_bf16 v[104:107], v[170:173], v[206:209], v[104:107]
	v_mfma_f32_16x16x32_bf16 v[108:111], v[152:155], v[206:209], v[108:111]
	v_mfma_f32_16x16x32_bf16 v[92:95], v[152:155], v[214:217], v[92:95]
	v_mfma_f32_16x16x32_bf16 v[88:91], v[170:173], v[214:217], v[88:91]
	v_mfma_f32_16x16x32_bf16 v[72:75], v[170:173], v[222:225], v[72:75]
	v_mfma_f32_16x16x32_bf16 v[76:79], v[152:155], v[222:225], v[76:79]
	v_mfma_f32_16x16x32_bf16 v[124:127], v[166:169], v[202:205], v[124:127]
	v_mfma_f32_16x16x32_bf16 v[120:123], v[174:177], v[202:205], v[120:123]
	v_mfma_f32_16x16x32_bf16 v[104:107], v[174:177], v[210:213], v[104:107]
	v_mfma_f32_16x16x32_bf16 v[108:111], v[166:169], v[210:213], v[108:111]
	v_mfma_f32_16x16x32_bf16 v[92:95], v[166:169], v[218:221], v[92:95]
	v_mfma_f32_16x16x32_bf16 v[88:91], v[174:177], v[218:221], v[88:91]
	v_mfma_f32_16x16x32_bf16 v[72:75], v[174:177], v[226:229], v[72:75]
	v_mfma_f32_16x16x32_bf16 v[76:79], v[166:169], v[226:229], v[76:79]
	v_mfma_f32_16x16x32_bf16 v[116:119], v[178:181], v[198:201], v[116:119]
	v_mfma_f32_16x16x32_bf16 v[112:115], v[186:189], v[198:201], v[112:115]
	v_mfma_f32_16x16x32_bf16 v[96:99], v[186:189], v[206:209], v[96:99]
	v_mfma_f32_16x16x32_bf16 v[100:103], v[178:181], v[206:209], v[100:103]
	v_mfma_f32_16x16x32_bf16 v[84:87], v[178:181], v[214:217], v[84:87]
	v_mfma_f32_16x16x32_bf16 v[80:83], v[186:189], v[214:217], v[80:83]
	v_mfma_f32_16x16x32_bf16 v[64:67], v[186:189], v[222:225], v[64:67]
	v_mfma_f32_16x16x32_bf16 v[68:71], v[178:181], v[222:225], v[68:71]
	v_mfma_f32_16x16x32_bf16 v[116:119], v[182:185], v[202:205], v[116:119]
	v_mfma_f32_16x16x32_bf16 v[112:115], v[194:197], v[202:205], v[112:115]
	v_mfma_f32_16x16x32_bf16 v[96:99], v[194:197], v[210:213], v[96:99]
	v_mfma_f32_16x16x32_bf16 v[100:103], v[182:185], v[210:213], v[100:103]
	v_mfma_f32_16x16x32_bf16 v[84:87], v[182:185], v[218:221], v[84:87]
	v_mfma_f32_16x16x32_bf16 v[80:83], v[194:197], v[218:221], v[80:83]
	v_mfma_f32_16x16x32_bf16 v[64:67], v[194:197], v[226:229], v[64:67]
	v_mfma_f32_16x16x32_bf16 v[68:71], v[182:185], v[226:229], v[68:71]
	s_barrier
	s_add_i32 s28, s60, s42
	v_lshl_add_u64 v[156:157], s[34:35], 0, v[130:131]
	s_mov_b32 m0, s28
	ds_read_b128 v[198:201], v163 offset:16384
	ds_read_b128 v[202:205], v163 offset:17408
	ds_read_b128 v[206:209], v163 offset:18432
	ds_read_b128 v[210:213], v163 offset:19456
	ds_read_b128 v[214:217], v163 offset:20480
	ds_read_b128 v[218:221], v163 offset:21504
	ds_read_b128 v[222:225], v163 offset:22528
	ds_read_b128 v[226:229], v163 offset:23552
	global_load_lds_dwordx4 v[156:157], off
	s_add_i32 m0, s28, 0x2000
	s_add_u32 s28, s34, 0x160000
	v_lshl_add_u64 v[190:191], s[34:35], 0, v[134:135]
	s_addc_u32 s29, s35, 0
	s_add_i32 s33, s61, s42
	global_load_lds_dwordx4 v[190:191], off
	v_lshl_add_u64 v[230:231], s[28:29], 0, v[130:131]
	s_mov_b32 m0, s33
	v_lshl_add_u64 v[232:233], s[36:37], 0, v[132:133]
	global_load_lds_dwordx4 v[230:231], off
	v_lshl_add_u64 v[230:231], s[28:29], 0, v[134:135]
	s_add_i32 m0, s33, 0x2000
	s_nop 0
	global_load_lds_dwordx4 v[230:231], off
	v_lshl_add_u64 v[230:231], s[36:37], 0, v[128:129]
	s_mov_b32 m0, s43
	s_nop 0
	global_load_lds_dwordx4 v[230:231], off
	s_mov_b32 m0, s48
	s_nop 0
	global_load_lds_dwordx4 v[232:233], off
	s_waitcnt vmcnt(8)
	s_waitcnt lgkmcnt(0)
	s_barrier
	s_waitcnt lgkmcnt(0)
	v_mfma_f32_16x16x32_bf16 v[60:63], v[152:155], v[198:201], v[60:63]
	v_mfma_f32_16x16x32_bf16 v[56:59], v[170:173], v[198:201], v[56:59]
	v_mfma_f32_16x16x32_bf16 v[40:43], v[170:173], v[206:209], v[40:43]
	v_mfma_f32_16x16x32_bf16 v[44:47], v[152:155], v[206:209], v[44:47]
	v_mfma_f32_16x16x32_bf16 v[28:31], v[152:155], v[214:217], v[28:31]
	v_mfma_f32_16x16x32_bf16 v[24:27], v[170:173], v[214:217], v[24:27]
	v_mfma_f32_16x16x32_bf16 v[8:11], v[170:173], v[222:225], v[8:11]
	v_mfma_f32_16x16x32_bf16 v[12:15], v[152:155], v[222:225], v[12:15]
	v_mfma_f32_16x16x32_bf16 v[60:63], v[166:169], v[202:205], v[60:63]
	v_mfma_f32_16x16x32_bf16 v[56:59], v[174:177], v[202:205], v[56:59]
	v_mfma_f32_16x16x32_bf16 v[40:43], v[174:177], v[210:213], v[40:43]
	v_mfma_f32_16x16x32_bf16 v[44:47], v[166:169], v[210:213], v[44:47]
	v_mfma_f32_16x16x32_bf16 v[28:31], v[166:169], v[218:221], v[28:31]
	v_mfma_f32_16x16x32_bf16 v[24:27], v[174:177], v[218:221], v[24:27]
	v_mfma_f32_16x16x32_bf16 v[8:11], v[174:177], v[226:229], v[8:11]
	v_mfma_f32_16x16x32_bf16 v[12:15], v[166:169], v[226:229], v[12:15]
	v_mfma_f32_16x16x32_bf16 v[52:55], v[178:181], v[198:201], v[52:55]
	v_mfma_f32_16x16x32_bf16 v[48:51], v[186:189], v[198:201], v[48:51]
	v_mfma_f32_16x16x32_bf16 v[32:35], v[186:189], v[206:209], v[32:35]
	v_mfma_f32_16x16x32_bf16 v[36:39], v[178:181], v[206:209], v[36:39]
	v_mfma_f32_16x16x32_bf16 v[20:23], v[178:181], v[214:217], v[20:23]
	v_mfma_f32_16x16x32_bf16 v[16:19], v[186:189], v[214:217], v[16:19]
	v_mfma_f32_16x16x32_bf16 v[0:3], v[186:189], v[222:225], v[0:3]
	v_mfma_f32_16x16x32_bf16 v[4:7], v[178:181], v[222:225], v[4:7]
	v_mfma_f32_16x16x32_bf16 v[52:55], v[182:185], v[202:205], v[52:55]
	v_mfma_f32_16x16x32_bf16 v[48:51], v[194:197], v[202:205], v[48:51]
	v_mfma_f32_16x16x32_bf16 v[32:35], v[194:197], v[210:213], v[32:35]
	v_mfma_f32_16x16x32_bf16 v[36:39], v[182:185], v[210:213], v[36:39]
	v_mfma_f32_16x16x32_bf16 v[20:23], v[182:185], v[218:221], v[20:23]
	v_mfma_f32_16x16x32_bf16 v[16:19], v[194:197], v[218:221], v[16:19]
	v_mfma_f32_16x16x32_bf16 v[0:3], v[194:197], v[226:229], v[0:3]
	v_mfma_f32_16x16x32_bf16 v[4:7], v[182:185], v[226:229], v[4:7]
	s_barrier
	s_add_i32 s33, 0, 0x18000
	v_add_u32_e32 v165, s33, v159
	s_add_i32 s54, 0, 0x1c000
	ds_read_b128 v[152:155], v165
	ds_read_b128 v[166:169], v165 offset:1024
	ds_read_b128 v[170:173], v165 offset:2048
	ds_read_b128 v[174:177], v165 offset:3072
	v_add_u32_e32 v165, s54, v159
	ds_read_b128 v[178:181], v165
	ds_read_b128 v[182:185], v165 offset:1024
	ds_read_b128 v[186:189], v165 offset:2048
	ds_read_b128 v[194:197], v165 offset:3072
	s_add_u32 s28, s36, 0x160000
	s_addc_u32 s29, s37, 0
	s_mov_b32 m0, s49
	v_lshl_add_u64 v[234:235], s[28:29], 0, v[128:129]
	ds_read_b128 v[198:201], v163 offset:32768
	ds_read_b128 v[202:205], v163 offset:33792
	ds_read_b128 v[206:209], v163 offset:34816
	ds_read_b128 v[210:213], v163 offset:35840
	ds_read_b128 v[214:217], v163 offset:36864
	ds_read_b128 v[218:221], v163 offset:37888
	ds_read_b128 v[222:225], v163 offset:38912
	ds_read_b128 v[226:229], v163 offset:39936
	global_load_lds_dwordx4 v[234:235], off
	v_lshl_add_u64 v[234:235], s[28:29], 0, v[132:133]
	s_mov_b32 m0, s50
	s_nop 0
	global_load_lds_dwordx4 v[234:235], off
	s_waitcnt vmcnt(8)
	s_waitcnt lgkmcnt(0)
	s_barrier
	s_waitcnt lgkmcnt(0)
	v_mfma_f32_16x16x32_bf16 v[124:127], v[152:155], v[198:201], v[124:127]
	v_mfma_f32_16x16x32_bf16 v[120:123], v[170:173], v[198:201], v[120:123]
	v_mfma_f32_16x16x32_bf16 v[104:107], v[170:173], v[206:209], v[104:107]
	v_mfma_f32_16x16x32_bf16 v[108:111], v[152:155], v[206:209], v[108:111]
	v_mfma_f32_16x16x32_bf16 v[92:95], v[152:155], v[214:217], v[92:95]
	v_mfma_f32_16x16x32_bf16 v[88:91], v[170:173], v[214:217], v[88:91]
	v_mfma_f32_16x16x32_bf16 v[72:75], v[170:173], v[222:225], v[72:75]
	v_mfma_f32_16x16x32_bf16 v[76:79], v[152:155], v[222:225], v[76:79]
	v_mfma_f32_16x16x32_bf16 v[124:127], v[166:169], v[202:205], v[124:127]
	v_mfma_f32_16x16x32_bf16 v[120:123], v[174:177], v[202:205], v[120:123]
	v_mfma_f32_16x16x32_bf16 v[104:107], v[174:177], v[210:213], v[104:107]
	v_mfma_f32_16x16x32_bf16 v[108:111], v[166:169], v[210:213], v[108:111]
	v_mfma_f32_16x16x32_bf16 v[92:95], v[166:169], v[218:221], v[92:95]
	v_mfma_f32_16x16x32_bf16 v[88:91], v[174:177], v[218:221], v[88:91]
	v_mfma_f32_16x16x32_bf16 v[72:75], v[174:177], v[226:229], v[72:75]
	v_mfma_f32_16x16x32_bf16 v[76:79], v[166:169], v[226:229], v[76:79]
	v_mfma_f32_16x16x32_bf16 v[116:119], v[178:181], v[198:201], v[116:119]
	v_mfma_f32_16x16x32_bf16 v[112:115], v[186:189], v[198:201], v[112:115]
	v_mfma_f32_16x16x32_bf16 v[96:99], v[186:189], v[206:209], v[96:99]
	v_mfma_f32_16x16x32_bf16 v[100:103], v[178:181], v[206:209], v[100:103]
	v_mfma_f32_16x16x32_bf16 v[84:87], v[178:181], v[214:217], v[84:87]
	v_mfma_f32_16x16x32_bf16 v[80:83], v[186:189], v[214:217], v[80:83]
	v_mfma_f32_16x16x32_bf16 v[64:67], v[186:189], v[222:225], v[64:67]
	v_mfma_f32_16x16x32_bf16 v[68:71], v[178:181], v[222:225], v[68:71]
	v_mfma_f32_16x16x32_bf16 v[116:119], v[182:185], v[202:205], v[116:119]
	v_mfma_f32_16x16x32_bf16 v[112:115], v[194:197], v[202:205], v[112:115]
	v_mfma_f32_16x16x32_bf16 v[96:99], v[194:197], v[210:213], v[96:99]
	v_mfma_f32_16x16x32_bf16 v[100:103], v[182:185], v[210:213], v[100:103]
	v_mfma_f32_16x16x32_bf16 v[84:87], v[182:185], v[218:221], v[84:87]
	v_mfma_f32_16x16x32_bf16 v[80:83], v[194:197], v[218:221], v[80:83]
	v_mfma_f32_16x16x32_bf16 v[64:67], v[194:197], v[226:229], v[64:67]
	v_mfma_f32_16x16x32_bf16 v[68:71], v[182:185], v[226:229], v[68:71]
	s_barrier
	s_add_i32 s28, s33, s42
	v_lshl_add_u64 v[156:157], v[156:157], 0, s[22:23]
	s_mov_b32 m0, s28
	ds_read_b128 v[198:201], v163 offset:49152
	ds_read_b128 v[202:205], v163 offset:50176
	ds_read_b128 v[206:209], v163 offset:51200
	ds_read_b128 v[210:213], v163 offset:52224
	ds_read_b128 v[214:217], v163 offset:53248
	ds_read_b128 v[218:221], v163 offset:54272
	ds_read_b128 v[222:225], v163 offset:55296
	ds_read_b128 v[226:229], v163 offset:56320
	global_load_lds_dwordx4 v[156:157], off
	s_add_i32 m0, s28, 0x2000
	s_add_u32 s28, s34, 0x160080
	v_lshl_add_u64 v[156:157], v[190:191], 0, s[22:23]
	s_addc_u32 s29, s35, 0
	s_add_i32 s33, s54, s42
	global_load_lds_dwordx4 v[156:157], off
	v_lshl_add_u64 v[156:157], s[28:29], 0, v[130:131]
	s_mov_b32 m0, s33
	s_nop 0
	global_load_lds_dwordx4 v[156:157], off
	v_lshl_add_u64 v[156:157], s[28:29], 0, v[134:135]
	s_add_i32 m0, s33, 0x2000
	s_nop 0
	global_load_lds_dwordx4 v[156:157], off
	v_lshl_add_u64 v[156:157], v[230:231], 0, s[22:23]
	s_mov_b32 m0, s58
	s_nop 0
	global_load_lds_dwordx4 v[156:157], off
	v_lshl_add_u64 v[156:157], v[232:233], 0, s[22:23]
	s_mov_b32 m0, s59
	s_nop 0
	global_load_lds_dwordx4 v[156:157], off
	s_waitcnt vmcnt(8)
	s_waitcnt lgkmcnt(0)
	s_barrier
	s_waitcnt lgkmcnt(0)
	v_mfma_f32_16x16x32_bf16 v[60:63], v[152:155], v[198:201], v[60:63]
	v_mfma_f32_16x16x32_bf16 v[56:59], v[170:173], v[198:201], v[56:59]
	v_mfma_f32_16x16x32_bf16 v[40:43], v[170:173], v[206:209], v[40:43]
	v_mfma_f32_16x16x32_bf16 v[44:47], v[152:155], v[206:209], v[44:47]
	v_mfma_f32_16x16x32_bf16 v[28:31], v[152:155], v[214:217], v[28:31]
	v_mfma_f32_16x16x32_bf16 v[24:27], v[170:173], v[214:217], v[24:27]
	v_mfma_f32_16x16x32_bf16 v[8:11], v[170:173], v[222:225], v[8:11]
	v_mfma_f32_16x16x32_bf16 v[12:15], v[152:155], v[222:225], v[12:15]
	v_mfma_f32_16x16x32_bf16 v[60:63], v[166:169], v[202:205], v[60:63]
	v_mfma_f32_16x16x32_bf16 v[56:59], v[174:177], v[202:205], v[56:59]
	v_mfma_f32_16x16x32_bf16 v[40:43], v[174:177], v[210:213], v[40:43]
	v_mfma_f32_16x16x32_bf16 v[44:47], v[166:169], v[210:213], v[44:47]
	v_mfma_f32_16x16x32_bf16 v[28:31], v[166:169], v[218:221], v[28:31]
	v_mfma_f32_16x16x32_bf16 v[24:27], v[174:177], v[218:221], v[24:27]
	v_mfma_f32_16x16x32_bf16 v[8:11], v[174:177], v[226:229], v[8:11]
	v_mfma_f32_16x16x32_bf16 v[12:15], v[166:169], v[226:229], v[12:15]
	v_mfma_f32_16x16x32_bf16 v[52:55], v[178:181], v[198:201], v[52:55]
	v_mfma_f32_16x16x32_bf16 v[48:51], v[186:189], v[198:201], v[48:51]
	v_mfma_f32_16x16x32_bf16 v[32:35], v[186:189], v[206:209], v[32:35]
	v_mfma_f32_16x16x32_bf16 v[36:39], v[178:181], v[206:209], v[36:39]
	v_mfma_f32_16x16x32_bf16 v[20:23], v[178:181], v[214:217], v[20:23]
	v_mfma_f32_16x16x32_bf16 v[16:19], v[186:189], v[214:217], v[16:19]
	v_mfma_f32_16x16x32_bf16 v[0:3], v[186:189], v[222:225], v[0:3]
	v_mfma_f32_16x16x32_bf16 v[4:7], v[178:181], v[222:225], v[4:7]
	v_mfma_f32_16x16x32_bf16 v[52:55], v[182:185], v[202:205], v[52:55]
	v_mfma_f32_16x16x32_bf16 v[48:51], v[194:197], v[202:205], v[48:51]
	v_mfma_f32_16x16x32_bf16 v[32:35], v[194:197], v[210:213], v[32:35]
	v_mfma_f32_16x16x32_bf16 v[36:39], v[182:185], v[210:213], v[36:39]
	v_mfma_f32_16x16x32_bf16 v[20:23], v[182:185], v[218:221], v[20:23]
	v_mfma_f32_16x16x32_bf16 v[16:19], v[194:197], v[218:221], v[16:19]
	v_mfma_f32_16x16x32_bf16 v[0:3], v[194:197], v[226:229], v[0:3]
	v_mfma_f32_16x16x32_bf16 v[4:7], v[182:185], v[226:229], v[4:7]
	s_barrier
	s_add_i32 s68, s68, 2
	s_add_u32 s66, s66, 0x100
	s_addc_u32 s67, s67, 0
	s_cmpk_gt_u32 s68, 0x55
	s_mov_b64 s[28:29], s[30:31]
	s_cbranch_scc0 .LBB0_1187
	v_lshl_add_u32 v156, s64, 8, v158
	v_lshl_or_b32 v154, s65, 8, v160
	v_ashrrev_i32_e32 v157, 31, v156
	v_ashrrev_i32_e32 v155, 31, v154
	v_lshlrev_b64 v[152:153], 11, v[156:157]
	v_lshl_add_u64 v[152:153], v[152:153], 0, v[154:155]
	v_lshlrev_b64 v[170:171], 1, v[152:153]
	v_lshl_add_u64 v[172:173], s[16:17], 0, v[170:171]
	global_load_dwordx4 v[180:183], v[172:173], off
	global_load_dwordx4 v[184:187], v[172:173], off offset:256
	v_add_co_u32_e32 v252, vcc, 0x10000, v172
	s_nop 1
	v_addc_co_u32_e32 v253, vcc, 0, v173, vcc
	global_load_dwordx4 v[188:191], v[252:253], off
	global_load_dwordx4 v[194:197], v[252:253], off offset:256
	v_add_co_u32_e32 v254, vcc, 0x20000, v172
	s_nop 1
	v_addc_co_u32_e32 v255, vcc, 0, v173, vcc
	global_load_dwordx4 v[198:201], v[254:255], off
	global_load_dwordx4 v[202:205], v[254:255], off offset:256
	v_add_co_u32_e32 v252, vcc, 0x30000, v172
	s_nop 1
	v_addc_co_u32_e32 v253, vcc, 0, v173, vcc
	global_load_dwordx4 v[206:209], v[252:253], off
	global_load_dwordx4 v[210:213], v[252:253], off offset:256
	v_add_co_u32_e32 v254, vcc, 0x80000, v172
	s_nop 1
	v_addc_co_u32_e32 v255, vcc, 0, v173, vcc
	global_load_dwordx4 v[214:217], v[254:255], off
	global_load_dwordx4 v[218:221], v[254:255], off offset:256
	v_add_co_u32_e32 v252, vcc, 0x90000, v172
	s_nop 1
	v_addc_co_u32_e32 v253, vcc, 0, v173, vcc
	global_load_dwordx4 v[222:225], v[252:253], off
	global_load_dwordx4 v[226:229], v[252:253], off offset:256
	v_add_co_u32_e32 v254, vcc, 0xa0000, v172
	s_nop 1
	v_addc_co_u32_e32 v255, vcc, 0, v173, vcc
	global_load_dwordx4 v[230:233], v[254:255], off
	global_load_dwordx4 v[234:237], v[254:255], off offset:256
	v_add_co_u32_e32 v252, vcc, 0xb0000, v172
	s_nop 1
	v_addc_co_u32_e32 v253, vcc, 0, v173, vcc
	global_load_dwordx4 v[238:241], v[252:253], off
	global_load_dwordx4 v[242:245], v[252:253], off offset:256
	s_and_b64 vcc, exec, s[24:25]
	s_cbranch_vccz .LBB0_1190
	s_barrier

.LBB0_1271:
	ds_read_b128 v[144:147], v155
	ds_read_b128 v[148:151], v155 offset:1024
	ds_read_b128 v[160:163], v155 offset:2048
	ds_read_b128 v[164:167], v155 offset:3072
	ds_read_b128 v[168:171], v156
	ds_read_b128 v[172:175], v156 offset:1024
	ds_read_b128 v[176:179], v156 offset:2048
	ds_read_b128 v[180:183], v156 offset:3072
	s_add_u32 s33, s30, 0xfff80080
	s_addc_u32 s34, s31, -1
	s_cmp_eq_u32 s67, 28
	s_cselect_b32 s37, s25, s34
	s_cselect_b32 s36, s63, s33
	s_cselect_b32 s35, s23, s66
	s_cselect_b32 s34, s64, s65
	v_lshl_add_u64 v[218:219], s[30:31], 0, v[136:137]
	s_add_i32 m0, s48, 0xc000
	ds_read_b128 v[184:187], v157
	ds_read_b128 v[188:191], v157 offset:1024
	ds_read_b128 v[194:197], v157 offset:2048
	ds_read_b128 v[198:201], v157 offset:3072
	ds_read_b128 v[202:205], v157 offset:4096
	ds_read_b128 v[206:209], v157 offset:5120
	ds_read_b128 v[210:213], v157 offset:6144
	ds_read_b128 v[214:217], v157 offset:7168
	global_load_lds_dwordx4 v[218:219], off
	v_lshl_add_u64 v[218:219], s[30:31], 0, v[138:139]
	s_add_i32 m0, s48, 0xe000
	s_nop 0
	global_load_lds_dwordx4 v[218:219], off
	s_waitcnt vmcnt(8)
	s_waitcnt lgkmcnt(0)
	s_barrier
	s_waitcnt lgkmcnt(0)
	v_mfma_f32_16x16x32_bf16 v[124:127], v[144:147], v[184:187], v[124:127]
	v_mfma_f32_16x16x32_bf16 v[120:123], v[160:163], v[184:187], v[120:123]
	v_mfma_f32_16x16x32_bf16 v[104:107], v[160:163], v[194:197], v[104:107]
	v_mfma_f32_16x16x32_bf16 v[108:111], v[144:147], v[194:197], v[108:111]
	v_mfma_f32_16x16x32_bf16 v[92:95], v[144:147], v[202:205], v[92:95]
	v_mfma_f32_16x16x32_bf16 v[88:91], v[160:163], v[202:205], v[88:91]
	v_mfma_f32_16x16x32_bf16 v[72:75], v[160:163], v[210:213], v[72:75]
	v_mfma_f32_16x16x32_bf16 v[76:79], v[144:147], v[210:213], v[76:79]
	v_mfma_f32_16x16x32_bf16 v[124:127], v[148:151], v[188:191], v[124:127]
	v_mfma_f32_16x16x32_bf16 v[120:123], v[164:167], v[188:191], v[120:123]
	v_mfma_f32_16x16x32_bf16 v[104:107], v[164:167], v[198:201], v[104:107]
	v_mfma_f32_16x16x32_bf16 v[108:111], v[148:151], v[198:201], v[108:111]
	v_mfma_f32_16x16x32_bf16 v[92:95], v[148:151], v[206:209], v[92:95]
	v_mfma_f32_16x16x32_bf16 v[88:91], v[164:167], v[206:209], v[88:91]
	v_mfma_f32_16x16x32_bf16 v[72:75], v[164:167], v[214:217], v[72:75]
	v_mfma_f32_16x16x32_bf16 v[76:79], v[148:151], v[214:217], v[76:79]
	v_mfma_f32_16x16x32_bf16 v[116:119], v[168:171], v[184:187], v[116:119]
	v_mfma_f32_16x16x32_bf16 v[112:115], v[176:179], v[184:187], v[112:115]
	v_mfma_f32_16x16x32_bf16 v[96:99], v[176:179], v[194:197], v[96:99]
	v_mfma_f32_16x16x32_bf16 v[100:103], v[168:171], v[194:197], v[100:103]
	v_mfma_f32_16x16x32_bf16 v[84:87], v[168:171], v[202:205], v[84:87]
	v_mfma_f32_16x16x32_bf16 v[80:83], v[176:179], v[202:205], v[80:83]
	v_mfma_f32_16x16x32_bf16 v[64:67], v[176:179], v[210:213], v[64:67]
	v_mfma_f32_16x16x32_bf16 v[68:71], v[168:171], v[210:213], v[68:71]
	v_mfma_f32_16x16x32_bf16 v[116:119], v[172:175], v[188:191], v[116:119]
	v_mfma_f32_16x16x32_bf16 v[112:115], v[180:183], v[188:191], v[112:115]
	v_mfma_f32_16x16x32_bf16 v[96:99], v[180:183], v[198:201], v[96:99]
	v_mfma_f32_16x16x32_bf16 v[100:103], v[172:175], v[198:201], v[100:103]
	v_mfma_f32_16x16x32_bf16 v[84:87], v[172:175], v[206:209], v[84:87]
	v_mfma_f32_16x16x32_bf16 v[80:83], v[180:183], v[206:209], v[80:83]
	v_mfma_f32_16x16x32_bf16 v[64:67], v[180:183], v[214:217], v[64:67]
	v_mfma_f32_16x16x32_bf16 v[68:71], v[172:175], v[214:217], v[68:71]
	s_barrier
	s_add_i32 s33, s59, s42
	v_lshl_add_u64 v[218:219], s[34:35], 0, v[132:133]
	s_mov_b32 m0, s33
	ds_read_b128 v[184:187], v157 offset:16384
	ds_read_b128 v[188:191], v157 offset:17408
	ds_read_b128 v[194:197], v157 offset:18432
	ds_read_b128 v[198:201], v157 offset:19456
	ds_read_b128 v[202:205], v157 offset:20480
	ds_read_b128 v[206:209], v157 offset:21504
	ds_read_b128 v[210:213], v157 offset:22528
	ds_read_b128 v[214:217], v157 offset:23552
	global_load_lds_dwordx4 v[218:219], off
	s_add_i32 m0, s33, 0x2000
	s_add_u32 s54, s34, 0x80000
	v_lshl_add_u64 v[220:221], s[34:35], 0, v[128:129]
	s_addc_u32 s55, s35, 0
	s_add_i32 s33, s60, s42
	global_load_lds_dwordx4 v[220:221], off
	v_lshl_add_u64 v[222:223], s[54:55], 0, v[132:133]
	s_mov_b32 m0, s33
	v_lshl_add_u64 v[224:225], s[36:37], 0, v[130:131]
	global_load_lds_dwordx4 v[222:223], off
	v_lshl_add_u64 v[222:223], s[54:55], 0, v[128:129]
	s_add_i32 m0, s33, 0x2000
	s_nop 0
	global_load_lds_dwordx4 v[222:223], off
	v_lshl_add_u64 v[222:223], s[36:37], 0, v[134:135]
	s_mov_b32 m0, s48
	s_nop 0
	global_load_lds_dwordx4 v[222:223], off
	s_mov_b32 m0, s49
	s_nop 0
	global_load_lds_dwordx4 v[224:225], off
	s_waitcnt vmcnt(8)
	s_waitcnt lgkmcnt(0)
	s_barrier
	s_waitcnt lgkmcnt(0)
	v_mfma_f32_16x16x32_bf16 v[60:63], v[144:147], v[184:187], v[60:63]
	v_mfma_f32_16x16x32_bf16 v[56:59], v[160:163], v[184:187], v[56:59]
	v_mfma_f32_16x16x32_bf16 v[40:43], v[160:163], v[194:197], v[40:43]
	v_mfma_f32_16x16x32_bf16 v[44:47], v[144:147], v[194:197], v[44:47]
	v_mfma_f32_16x16x32_bf16 v[28:31], v[144:147], v[202:205], v[28:31]
	v_mfma_f32_16x16x32_bf16 v[24:27], v[160:163], v[202:205], v[24:27]
	v_mfma_f32_16x16x32_bf16 v[8:11], v[160:163], v[210:213], v[8:11]
	v_mfma_f32_16x16x32_bf16 v[12:15], v[144:147], v[210:213], v[12:15]
	v_mfma_f32_16x16x32_bf16 v[60:63], v[148:151], v[188:191], v[60:63]
	v_mfma_f32_16x16x32_bf16 v[56:59], v[164:167], v[188:191], v[56:59]
	v_mfma_f32_16x16x32_bf16 v[40:43], v[164:167], v[198:201], v[40:43]
	v_mfma_f32_16x16x32_bf16 v[44:47], v[148:151], v[198:201], v[44:47]
	v_mfma_f32_16x16x32_bf16 v[28:31], v[148:151], v[206:209], v[28:31]
	v_mfma_f32_16x16x32_bf16 v[24:27], v[164:167], v[206:209], v[24:27]
	v_mfma_f32_16x16x32_bf16 v[8:11], v[164:167], v[214:217], v[8:11]
	v_mfma_f32_16x16x32_bf16 v[12:15], v[148:151], v[214:217], v[12:15]
	v_mfma_f32_16x16x32_bf16 v[52:55], v[168:171], v[184:187], v[52:55]
	v_mfma_f32_16x16x32_bf16 v[48:51], v[176:179], v[184:187], v[48:51]
	v_mfma_f32_16x16x32_bf16 v[32:35], v[176:179], v[194:197], v[32:35]
	v_mfma_f32_16x16x32_bf16 v[36:39], v[168:171], v[194:197], v[36:39]
	v_mfma_f32_16x16x32_bf16 v[20:23], v[168:171], v[202:205], v[20:23]
	v_mfma_f32_16x16x32_bf16 v[16:19], v[176:179], v[202:205], v[16:19]
	v_mfma_f32_16x16x32_bf16 v[0:3], v[176:179], v[210:213], v[0:3]
	v_mfma_f32_16x16x32_bf16 v[4:7], v[168:171], v[210:213], v[4:7]
	v_mfma_f32_16x16x32_bf16 v[52:55], v[172:175], v[188:191], v[52:55]
	v_mfma_f32_16x16x32_bf16 v[48:51], v[180:183], v[188:191], v[48:51]
	v_mfma_f32_16x16x32_bf16 v[32:35], v[180:183], v[198:201], v[32:35]
	v_mfma_f32_16x16x32_bf16 v[36:39], v[172:175], v[198:201], v[36:39]
	v_mfma_f32_16x16x32_bf16 v[20:23], v[172:175], v[206:209], v[20:23]
	v_mfma_f32_16x16x32_bf16 v[16:19], v[180:183], v[206:209], v[16:19]
	v_mfma_f32_16x16x32_bf16 v[0:3], v[180:183], v[214:217], v[0:3]
	v_mfma_f32_16x16x32_bf16 v[4:7], v[172:175], v[214:217], v[4:7]
	s_barrier
	s_add_i32 s33, 0, 0x18000
	s_add_i32 s54, 0, 0x1c000
	v_add_u32_e32 v164, s33, v153
	v_add_u32_e32 v180, s54, v153
	ds_read_b128 v[144:147], v164
	ds_read_b128 v[148:151], v164 offset:1024
	ds_read_b128 v[160:163], v164 offset:2048
	ds_read_b128 v[164:167], v164 offset:3072
	ds_read_b128 v[168:171], v180
	ds_read_b128 v[172:175], v180 offset:1024
	ds_read_b128 v[176:179], v180 offset:2048
	ds_read_b128 v[180:183], v180 offset:3072
	s_add_u32 s36, s36, 0x80000
	s_addc_u32 s37, s37, 0
	s_mov_b32 m0, s50
	v_lshl_add_u64 v[226:227], s[36:37], 0, v[134:135]
	ds_read_b128 v[184:187], v157 offset:32768
	ds_read_b128 v[188:191], v157 offset:33792
	ds_read_b128 v[194:197], v157 offset:34816
	ds_read_b128 v[198:201], v157 offset:35840
	ds_read_b128 v[202:205], v157 offset:36864
	ds_read_b128 v[206:209], v157 offset:37888
	ds_read_b128 v[210:213], v157 offset:38912
	ds_read_b128 v[214:217], v157 offset:39936
	global_load_lds_dwordx4 v[226:227], off
	v_lshl_add_u64 v[226:227], s[36:37], 0, v[130:131]
	s_mov_b32 m0, s51
	s_nop 0
	global_load_lds_dwordx4 v[226:227], off
	s_waitcnt vmcnt(8)
	s_waitcnt lgkmcnt(0)
	s_barrier
	s_waitcnt lgkmcnt(0)
	v_mfma_f32_16x16x32_bf16 v[124:127], v[144:147], v[184:187], v[124:127]
	v_mfma_f32_16x16x32_bf16 v[120:123], v[160:163], v[184:187], v[120:123]
	v_mfma_f32_16x16x32_bf16 v[104:107], v[160:163], v[194:197], v[104:107]
	v_mfma_f32_16x16x32_bf16 v[108:111], v[144:147], v[194:197], v[108:111]
	v_mfma_f32_16x16x32_bf16 v[92:95], v[144:147], v[202:205], v[92:95]
	v_mfma_f32_16x16x32_bf16 v[88:91], v[160:163], v[202:205], v[88:91]
	v_mfma_f32_16x16x32_bf16 v[72:75], v[160:163], v[210:213], v[72:75]
	v_mfma_f32_16x16x32_bf16 v[76:79], v[144:147], v[210:213], v[76:79]
	v_mfma_f32_16x16x32_bf16 v[124:127], v[148:151], v[188:191], v[124:127]
	v_mfma_f32_16x16x32_bf16 v[120:123], v[164:167], v[188:191], v[120:123]
	v_mfma_f32_16x16x32_bf16 v[104:107], v[164:167], v[198:201], v[104:107]
	v_mfma_f32_16x16x32_bf16 v[108:111], v[148:151], v[198:201], v[108:111]
	v_mfma_f32_16x16x32_bf16 v[92:95], v[148:151], v[206:209], v[92:95]
	v_mfma_f32_16x16x32_bf16 v[88:91], v[164:167], v[206:209], v[88:91]
	v_mfma_f32_16x16x32_bf16 v[72:75], v[164:167], v[214:217], v[72:75]
	v_mfma_f32_16x16x32_bf16 v[76:79], v[148:151], v[214:217], v[76:79]
	v_mfma_f32_16x16x32_bf16 v[116:119], v[168:171], v[184:187], v[116:119]
	v_mfma_f32_16x16x32_bf16 v[112:115], v[176:179], v[184:187], v[112:115]
	v_mfma_f32_16x16x32_bf16 v[96:99], v[176:179], v[194:197], v[96:99]
	v_mfma_f32_16x16x32_bf16 v[100:103], v[168:171], v[194:197], v[100:103]
	v_mfma_f32_16x16x32_bf16 v[84:87], v[168:171], v[202:205], v[84:87]
	v_mfma_f32_16x16x32_bf16 v[80:83], v[176:179], v[202:205], v[80:83]
	v_mfma_f32_16x16x32_bf16 v[64:67], v[176:179], v[210:213], v[64:67]
	v_mfma_f32_16x16x32_bf16 v[68:71], v[168:171], v[210:213], v[68:71]
	v_mfma_f32_16x16x32_bf16 v[116:119], v[172:175], v[188:191], v[116:119]
	v_mfma_f32_16x16x32_bf16 v[112:115], v[180:183], v[188:191], v[112:115]
	v_mfma_f32_16x16x32_bf16 v[96:99], v[180:183], v[198:201], v[96:99]
	v_mfma_f32_16x16x32_bf16 v[100:103], v[172:175], v[198:201], v[100:103]
	v_mfma_f32_16x16x32_bf16 v[84:87], v[172:175], v[206:209], v[84:87]
	v_mfma_f32_16x16x32_bf16 v[80:83], v[180:183], v[206:209], v[80:83]
	v_mfma_f32_16x16x32_bf16 v[64:67], v[180:183], v[214:217], v[64:67]
	v_mfma_f32_16x16x32_bf16 v[68:71], v[172:175], v[214:217], v[68:71]
	s_barrier
	s_add_i32 s33, s33, s42
	v_lshl_add_u64 v[218:219], v[218:219], 0, s[18:19]
	s_mov_b32 m0, s33
	ds_read_b128 v[184:187], v157 offset:49152
	ds_read_b128 v[188:191], v157 offset:50176
	ds_read_b128 v[194:197], v157 offset:51200
	ds_read_b128 v[198:201], v157 offset:52224
	ds_read_b128 v[202:205], v157 offset:53248
	ds_read_b128 v[206:209], v157 offset:54272
	ds_read_b128 v[210:213], v157 offset:55296
	ds_read_b128 v[214:217], v157 offset:56320
	global_load_lds_dwordx4 v[218:219], off
	s_add_i32 m0, s33, 0x2000
	s_add_u32 s34, s34, 0x80080
	v_lshl_add_u64 v[218:219], v[220:221], 0, s[18:19]
	s_addc_u32 s35, s35, 0
	s_add_i32 s33, s54, s42
	global_load_lds_dwordx4 v[218:219], off
	v_lshl_add_u64 v[218:219], s[34:35], 0, v[132:133]
	s_mov_b32 m0, s33
	s_nop 0
	global_load_lds_dwordx4 v[218:219], off
	v_lshl_add_u64 v[218:219], s[34:35], 0, v[128:129]
	s_add_i32 m0, s33, 0x2000
	s_nop 0
	global_load_lds_dwordx4 v[218:219], off
	v_lshl_add_u64 v[218:219], v[222:223], 0, s[18:19]
	s_mov_b32 m0, s57
	s_nop 0
	global_load_lds_dwordx4 v[218:219], off
	v_lshl_add_u64 v[218:219], v[224:225], 0, s[18:19]
	s_mov_b32 m0, s58
	s_nop 0
	global_load_lds_dwordx4 v[218:219], off
	s_waitcnt vmcnt(8)
	s_waitcnt lgkmcnt(0)
	s_barrier
	s_waitcnt lgkmcnt(0)
	v_mfma_f32_16x16x32_bf16 v[60:63], v[144:147], v[184:187], v[60:63]
	v_mfma_f32_16x16x32_bf16 v[56:59], v[160:163], v[184:187], v[56:59]
	v_mfma_f32_16x16x32_bf16 v[40:43], v[160:163], v[194:197], v[40:43]
	v_mfma_f32_16x16x32_bf16 v[44:47], v[144:147], v[194:197], v[44:47]
	v_mfma_f32_16x16x32_bf16 v[28:31], v[144:147], v[202:205], v[28:31]
	v_mfma_f32_16x16x32_bf16 v[24:27], v[160:163], v[202:205], v[24:27]
	v_mfma_f32_16x16x32_bf16 v[8:11], v[160:163], v[210:213], v[8:11]
	v_mfma_f32_16x16x32_bf16 v[12:15], v[144:147], v[210:213], v[12:15]
	v_mfma_f32_16x16x32_bf16 v[60:63], v[148:151], v[188:191], v[60:63]
	v_mfma_f32_16x16x32_bf16 v[56:59], v[164:167], v[188:191], v[56:59]
	v_mfma_f32_16x16x32_bf16 v[40:43], v[164:167], v[198:201], v[40:43]
	v_mfma_f32_16x16x32_bf16 v[44:47], v[148:151], v[198:201], v[44:47]
	v_mfma_f32_16x16x32_bf16 v[28:31], v[148:151], v[206:209], v[28:31]
	v_mfma_f32_16x16x32_bf16 v[24:27], v[164:167], v[206:209], v[24:27]
	v_mfma_f32_16x16x32_bf16 v[8:11], v[164:167], v[214:217], v[8:11]
	v_mfma_f32_16x16x32_bf16 v[12:15], v[148:151], v[214:217], v[12:15]
	v_mfma_f32_16x16x32_bf16 v[52:55], v[168:171], v[184:187], v[52:55]
	v_mfma_f32_16x16x32_bf16 v[48:51], v[176:179], v[184:187], v[48:51]
	v_mfma_f32_16x16x32_bf16 v[32:35], v[176:179], v[194:197], v[32:35]
	v_mfma_f32_16x16x32_bf16 v[36:39], v[168:171], v[194:197], v[36:39]
	v_mfma_f32_16x16x32_bf16 v[20:23], v[168:171], v[202:205], v[20:23]
	v_mfma_f32_16x16x32_bf16 v[16:19], v[176:179], v[202:205], v[16:19]
	v_mfma_f32_16x16x32_bf16 v[0:3], v[176:179], v[210:213], v[0:3]
	v_mfma_f32_16x16x32_bf16 v[4:7], v[168:171], v[210:213], v[4:7]
	v_mfma_f32_16x16x32_bf16 v[52:55], v[172:175], v[188:191], v[52:55]
	v_mfma_f32_16x16x32_bf16 v[48:51], v[180:183], v[188:191], v[48:51]
	v_mfma_f32_16x16x32_bf16 v[32:35], v[180:183], v[198:201], v[32:35]
	v_mfma_f32_16x16x32_bf16 v[36:39], v[172:175], v[198:201], v[36:39]
	v_mfma_f32_16x16x32_bf16 v[20:23], v[172:175], v[206:209], v[20:23]
	v_mfma_f32_16x16x32_bf16 v[16:19], v[180:183], v[206:209], v[16:19]
	v_mfma_f32_16x16x32_bf16 v[0:3], v[180:183], v[214:217], v[0:3]
	v_mfma_f32_16x16x32_bf16 v[4:7], v[172:175], v[214:217], v[4:7]
	s_barrier
	s_add_i32 s67, s67, 2
	s_add_u32 s30, s30, 0x100
	s_addc_u32 s31, s31, 0
	s_add_u32 s65, s65, 0x100
	s_addc_u32 s66, s66, 0
	s_cmp_gt_u32 s67, 29
	s_cbranch_scc0 .LBB0_1271
	v_lshl_add_u32 v144, s8, 8, v152
	v_ashrrev_i32_e32 v145, 31, v144
	v_lshl_add_u64 v[150:151], v[144:145], 2, s[16:17]
	global_load_dword v172, v[150:151], off
	global_load_dword v173, v[150:151], off offset:64
	global_load_dword v174, v[150:151], off offset:128
	global_load_dword v175, v[150:151], off offset:192
	global_load_dword v176, v[150:151], off offset:512
	global_load_dword v177, v[150:151], off offset:576
	global_load_dword v178, v[150:151], off offset:640
	global_load_dword v179, v[150:151], off offset:704
	s_and_b64 vcc, exec, s[20:21]
	s_cbranch_vccz .LBB0_1274
	s_barrier

.LBB0_1420:
	ds_read_b128 v[152:155], v161
	ds_read_b128 v[166:169], v161 offset:1024
	ds_read_b128 v[170:173], v161 offset:2048
	ds_read_b128 v[174:177], v161 offset:3072
	ds_read_b128 v[178:181], v162
	ds_read_b128 v[182:185], v162 offset:1024
	ds_read_b128 v[186:189], v162 offset:2048
	ds_read_b128 v[194:197], v162 offset:3072
	s_add_u32 s33, s38, 0xfff80080
	s_addc_u32 s40, s39, -1
	s_cmp_eq_u32 s68, 28
	s_cselect_b32 s43, s27, s40
	s_cselect_b32 s42, s35, s33
	s_cselect_b32 s41, s25, s67
	s_cselect_b32 s40, s65, s66
	v_lshl_add_u64 v[156:157], s[38:39], 0, v[136:137]
	s_add_i32 m0, s37, 0xc000
	ds_read_b128 v[198:201], v163
	ds_read_b128 v[202:205], v163 offset:1024
	ds_read_b128 v[206:209], v163 offset:2048
	ds_read_b128 v[210:213], v163 offset:3072
	ds_read_b128 v[214:217], v163 offset:4096
	ds_read_b128 v[218:221], v163 offset:5120
	ds_read_b128 v[222:225], v163 offset:6144
	ds_read_b128 v[226:229], v163 offset:7168
	global_load_lds_dwordx4 v[156:157], off
	v_lshl_add_u64 v[156:157], s[38:39], 0, v[138:139]
	s_add_i32 m0, s37, 0xe000
	s_nop 0
	global_load_lds_dwordx4 v[156:157], off
	s_waitcnt vmcnt(8)
	s_waitcnt lgkmcnt(0)
	s_barrier
	s_waitcnt lgkmcnt(0)
	v_mfma_f32_16x16x32_bf16 v[124:127], v[152:155], v[198:201], v[124:127]
	v_mfma_f32_16x16x32_bf16 v[120:123], v[170:173], v[198:201], v[120:123]
	v_mfma_f32_16x16x32_bf16 v[104:107], v[170:173], v[206:209], v[104:107]
	v_mfma_f32_16x16x32_bf16 v[108:111], v[152:155], v[206:209], v[108:111]
	v_mfma_f32_16x16x32_bf16 v[92:95], v[152:155], v[214:217], v[92:95]
	v_mfma_f32_16x16x32_bf16 v[88:91], v[170:173], v[214:217], v[88:91]
	v_mfma_f32_16x16x32_bf16 v[72:75], v[170:173], v[222:225], v[72:75]
	v_mfma_f32_16x16x32_bf16 v[76:79], v[152:155], v[222:225], v[76:79]
	v_mfma_f32_16x16x32_bf16 v[124:127], v[166:169], v[202:205], v[124:127]
	v_mfma_f32_16x16x32_bf16 v[120:123], v[174:177], v[202:205], v[120:123]
	v_mfma_f32_16x16x32_bf16 v[104:107], v[174:177], v[210:213], v[104:107]
	v_mfma_f32_16x16x32_bf16 v[108:111], v[166:169], v[210:213], v[108:111]
	v_mfma_f32_16x16x32_bf16 v[92:95], v[166:169], v[218:221], v[92:95]
	v_mfma_f32_16x16x32_bf16 v[88:91], v[174:177], v[218:221], v[88:91]
	v_mfma_f32_16x16x32_bf16 v[72:75], v[174:177], v[226:229], v[72:75]
	v_mfma_f32_16x16x32_bf16 v[76:79], v[166:169], v[226:229], v[76:79]
	v_mfma_f32_16x16x32_bf16 v[116:119], v[178:181], v[198:201], v[116:119]
	v_mfma_f32_16x16x32_bf16 v[112:115], v[186:189], v[198:201], v[112:115]
	v_mfma_f32_16x16x32_bf16 v[96:99], v[186:189], v[206:209], v[96:99]
	v_mfma_f32_16x16x32_bf16 v[100:103], v[178:181], v[206:209], v[100:103]
	v_mfma_f32_16x16x32_bf16 v[84:87], v[178:181], v[214:217], v[84:87]
	v_mfma_f32_16x16x32_bf16 v[80:83], v[186:189], v[214:217], v[80:83]
	v_mfma_f32_16x16x32_bf16 v[64:67], v[186:189], v[222:225], v[64:67]
	v_mfma_f32_16x16x32_bf16 v[68:71], v[178:181], v[222:225], v[68:71]
	v_mfma_f32_16x16x32_bf16 v[116:119], v[182:185], v[202:205], v[116:119]
	v_mfma_f32_16x16x32_bf16 v[112:115], v[194:197], v[202:205], v[112:115]
	v_mfma_f32_16x16x32_bf16 v[96:99], v[194:197], v[210:213], v[96:99]
	v_mfma_f32_16x16x32_bf16 v[100:103], v[182:185], v[210:213], v[100:103]
	v_mfma_f32_16x16x32_bf16 v[84:87], v[182:185], v[218:221], v[84:87]
	v_mfma_f32_16x16x32_bf16 v[80:83], v[194:197], v[218:221], v[80:83]
	v_mfma_f32_16x16x32_bf16 v[64:67], v[194:197], v[226:229], v[64:67]
	v_mfma_f32_16x16x32_bf16 v[68:71], v[182:185], v[226:229], v[68:71]
	s_barrier
	s_add_i32 s33, s63, s56
	v_lshl_add_u64 v[156:157], s[40:41], 0, v[130:131]
	s_mov_b32 m0, s33
	ds_read_b128 v[198:201], v163 offset:16384
	ds_read_b128 v[202:205], v163 offset:17408
	ds_read_b128 v[206:209], v163 offset:18432
	ds_read_b128 v[210:213], v163 offset:19456
	ds_read_b128 v[214:217], v163 offset:20480
	ds_read_b128 v[218:221], v163 offset:21504
	ds_read_b128 v[222:225], v163 offset:22528
	ds_read_b128 v[226:229], v163 offset:23552
	global_load_lds_dwordx4 v[156:157], off
	s_add_i32 m0, s33, 0x2000
	s_add_u32 s54, s40, 0x80000
	v_lshl_add_u64 v[190:191], s[40:41], 0, v[134:135]
	s_addc_u32 s55, s41, 0
	s_add_i32 s33, s64, s56
	global_load_lds_dwordx4 v[190:191], off
	v_lshl_add_u64 v[230:231], s[54:55], 0, v[130:131]
	s_mov_b32 m0, s33
	v_lshl_add_u64 v[232:233], s[42:43], 0, v[132:133]
	global_load_lds_dwordx4 v[230:231], off
	v_lshl_add_u64 v[230:231], s[54:55], 0, v[134:135]
	s_add_i32 m0, s33, 0x2000
	s_nop 0
	global_load_lds_dwordx4 v[230:231], off
	v_lshl_add_u64 v[230:231], s[42:43], 0, v[128:129]
	s_mov_b32 m0, s37
	s_nop 0
	global_load_lds_dwordx4 v[230:231], off
	s_mov_b32 m0, s57
	s_nop 0
	global_load_lds_dwordx4 v[232:233], off
	s_waitcnt vmcnt(8)
	s_waitcnt lgkmcnt(0)
	s_barrier
	s_waitcnt lgkmcnt(0)
	v_mfma_f32_16x16x32_bf16 v[60:63], v[152:155], v[198:201], v[60:63]
	v_mfma_f32_16x16x32_bf16 v[56:59], v[170:173], v[198:201], v[56:59]
	v_mfma_f32_16x16x32_bf16 v[40:43], v[170:173], v[206:209], v[40:43]
	v_mfma_f32_16x16x32_bf16 v[44:47], v[152:155], v[206:209], v[44:47]
	v_mfma_f32_16x16x32_bf16 v[28:31], v[152:155], v[214:217], v[28:31]
	v_mfma_f32_16x16x32_bf16 v[24:27], v[170:173], v[214:217], v[24:27]
	v_mfma_f32_16x16x32_bf16 v[8:11], v[170:173], v[222:225], v[8:11]
	v_mfma_f32_16x16x32_bf16 v[12:15], v[152:155], v[222:225], v[12:15]
	v_mfma_f32_16x16x32_bf16 v[60:63], v[166:169], v[202:205], v[60:63]
	v_mfma_f32_16x16x32_bf16 v[56:59], v[174:177], v[202:205], v[56:59]
	v_mfma_f32_16x16x32_bf16 v[40:43], v[174:177], v[210:213], v[40:43]
	v_mfma_f32_16x16x32_bf16 v[44:47], v[166:169], v[210:213], v[44:47]
	v_mfma_f32_16x16x32_bf16 v[28:31], v[166:169], v[218:221], v[28:31]
	v_mfma_f32_16x16x32_bf16 v[24:27], v[174:177], v[218:221], v[24:27]
	v_mfma_f32_16x16x32_bf16 v[8:11], v[174:177], v[226:229], v[8:11]
	v_mfma_f32_16x16x32_bf16 v[12:15], v[166:169], v[226:229], v[12:15]
	v_mfma_f32_16x16x32_bf16 v[52:55], v[178:181], v[198:201], v[52:55]
	v_mfma_f32_16x16x32_bf16 v[48:51], v[186:189], v[198:201], v[48:51]
	v_mfma_f32_16x16x32_bf16 v[32:35], v[186:189], v[206:209], v[32:35]
	v_mfma_f32_16x16x32_bf16 v[36:39], v[178:181], v[206:209], v[36:39]
	v_mfma_f32_16x16x32_bf16 v[20:23], v[178:181], v[214:217], v[20:23]
	v_mfma_f32_16x16x32_bf16 v[16:19], v[186:189], v[214:217], v[16:19]
	v_mfma_f32_16x16x32_bf16 v[0:3], v[186:189], v[222:225], v[0:3]
	v_mfma_f32_16x16x32_bf16 v[4:7], v[178:181], v[222:225], v[4:7]
	v_mfma_f32_16x16x32_bf16 v[52:55], v[182:185], v[202:205], v[52:55]
	v_mfma_f32_16x16x32_bf16 v[48:51], v[194:197], v[202:205], v[48:51]
	v_mfma_f32_16x16x32_bf16 v[32:35], v[194:197], v[210:213], v[32:35]
	v_mfma_f32_16x16x32_bf16 v[36:39], v[182:185], v[210:213], v[36:39]
	v_mfma_f32_16x16x32_bf16 v[20:23], v[182:185], v[218:221], v[20:23]
	v_mfma_f32_16x16x32_bf16 v[16:19], v[194:197], v[218:221], v[16:19]
	v_mfma_f32_16x16x32_bf16 v[0:3], v[194:197], v[226:229], v[0:3]
	v_mfma_f32_16x16x32_bf16 v[4:7], v[182:185], v[226:229], v[4:7]
	s_barrier
	s_add_i32 s33, 0, 0x18000
	v_add_u32_e32 v165, s33, v159
	s_add_i32 s54, 0, 0x1c000
	ds_read_b128 v[152:155], v165
	ds_read_b128 v[166:169], v165 offset:1024
	ds_read_b128 v[170:173], v165 offset:2048
	ds_read_b128 v[174:177], v165 offset:3072
	v_add_u32_e32 v165, s54, v159
	ds_read_b128 v[178:181], v165
	ds_read_b128 v[182:185], v165 offset:1024
	ds_read_b128 v[186:189], v165 offset:2048
	ds_read_b128 v[194:197], v165 offset:3072
	s_add_u32 s42, s42, 0x80000
	s_addc_u32 s43, s43, 0
	s_mov_b32 m0, s58
	v_lshl_add_u64 v[234:235], s[42:43], 0, v[128:129]
	ds_read_b128 v[198:201], v163 offset:32768
	ds_read_b128 v[202:205], v163 offset:33792
	ds_read_b128 v[206:209], v163 offset:34816
	ds_read_b128 v[210:213], v163 offset:35840
	ds_read_b128 v[214:217], v163 offset:36864
	ds_read_b128 v[218:221], v163 offset:37888
	ds_read_b128 v[222:225], v163 offset:38912
	ds_read_b128 v[226:229], v163 offset:39936
	global_load_lds_dwordx4 v[234:235], off
	v_lshl_add_u64 v[234:235], s[42:43], 0, v[132:133]
	s_mov_b32 m0, s59
	s_nop 0
	global_load_lds_dwordx4 v[234:235], off
	s_waitcnt vmcnt(8)
	s_waitcnt lgkmcnt(0)
	s_barrier
	s_waitcnt lgkmcnt(0)
	v_mfma_f32_16x16x32_bf16 v[124:127], v[152:155], v[198:201], v[124:127]
	v_mfma_f32_16x16x32_bf16 v[120:123], v[170:173], v[198:201], v[120:123]
	v_mfma_f32_16x16x32_bf16 v[104:107], v[170:173], v[206:209], v[104:107]
	v_mfma_f32_16x16x32_bf16 v[108:111], v[152:155], v[206:209], v[108:111]
	v_mfma_f32_16x16x32_bf16 v[92:95], v[152:155], v[214:217], v[92:95]
	v_mfma_f32_16x16x32_bf16 v[88:91], v[170:173], v[214:217], v[88:91]
	v_mfma_f32_16x16x32_bf16 v[72:75], v[170:173], v[222:225], v[72:75]
	v_mfma_f32_16x16x32_bf16 v[76:79], v[152:155], v[222:225], v[76:79]
	v_mfma_f32_16x16x32_bf16 v[124:127], v[166:169], v[202:205], v[124:127]
	v_mfma_f32_16x16x32_bf16 v[120:123], v[174:177], v[202:205], v[120:123]
	v_mfma_f32_16x16x32_bf16 v[104:107], v[174:177], v[210:213], v[104:107]
	v_mfma_f32_16x16x32_bf16 v[108:111], v[166:169], v[210:213], v[108:111]
	v_mfma_f32_16x16x32_bf16 v[92:95], v[166:169], v[218:221], v[92:95]
	v_mfma_f32_16x16x32_bf16 v[88:91], v[174:177], v[218:221], v[88:91]
	v_mfma_f32_16x16x32_bf16 v[72:75], v[174:177], v[226:229], v[72:75]
	v_mfma_f32_16x16x32_bf16 v[76:79], v[166:169], v[226:229], v[76:79]
	v_mfma_f32_16x16x32_bf16 v[116:119], v[178:181], v[198:201], v[116:119]
	v_mfma_f32_16x16x32_bf16 v[112:115], v[186:189], v[198:201], v[112:115]
	v_mfma_f32_16x16x32_bf16 v[96:99], v[186:189], v[206:209], v[96:99]
	v_mfma_f32_16x16x32_bf16 v[100:103], v[178:181], v[206:209], v[100:103]
	v_mfma_f32_16x16x32_bf16 v[84:87], v[178:181], v[214:217], v[84:87]
	v_mfma_f32_16x16x32_bf16 v[80:83], v[186:189], v[214:217], v[80:83]
	v_mfma_f32_16x16x32_bf16 v[64:67], v[186:189], v[222:225], v[64:67]
	v_mfma_f32_16x16x32_bf16 v[68:71], v[178:181], v[222:225], v[68:71]
	v_mfma_f32_16x16x32_bf16 v[116:119], v[182:185], v[202:205], v[116:119]
	v_mfma_f32_16x16x32_bf16 v[112:115], v[194:197], v[202:205], v[112:115]
	v_mfma_f32_16x16x32_bf16 v[96:99], v[194:197], v[210:213], v[96:99]
	v_mfma_f32_16x16x32_bf16 v[100:103], v[182:185], v[210:213], v[100:103]
	v_mfma_f32_16x16x32_bf16 v[84:87], v[182:185], v[218:221], v[84:87]
	v_mfma_f32_16x16x32_bf16 v[80:83], v[194:197], v[218:221], v[80:83]
	v_mfma_f32_16x16x32_bf16 v[64:67], v[194:197], v[226:229], v[64:67]
	v_mfma_f32_16x16x32_bf16 v[68:71], v[182:185], v[226:229], v[68:71]
	s_barrier
	s_add_i32 s33, s33, s56
	v_lshl_add_u64 v[156:157], v[156:157], 0, s[20:21]
	s_mov_b32 m0, s33
	ds_read_b128 v[198:201], v163 offset:49152
	ds_read_b128 v[202:205], v163 offset:50176
	ds_read_b128 v[206:209], v163 offset:51200
	ds_read_b128 v[210:213], v163 offset:52224
	ds_read_b128 v[214:217], v163 offset:53248
	ds_read_b128 v[218:221], v163 offset:54272
	ds_read_b128 v[222:225], v163 offset:55296
	ds_read_b128 v[226:229], v163 offset:56320
	global_load_lds_dwordx4 v[156:157], off
	s_add_i32 m0, s33, 0x2000
	s_add_u32 s40, s40, 0x80080
	v_lshl_add_u64 v[156:157], v[190:191], 0, s[20:21]
	s_addc_u32 s41, s41, 0
	s_add_i32 s33, s54, s56
	global_load_lds_dwordx4 v[156:157], off
	v_lshl_add_u64 v[156:157], s[40:41], 0, v[130:131]
	s_mov_b32 m0, s33
	s_nop 0
	global_load_lds_dwordx4 v[156:157], off
	v_lshl_add_u64 v[156:157], s[40:41], 0, v[134:135]
	s_add_i32 m0, s33, 0x2000
	s_nop 0
	global_load_lds_dwordx4 v[156:157], off
	v_lshl_add_u64 v[156:157], v[230:231], 0, s[20:21]
	s_mov_b32 m0, s61
	s_nop 0
	global_load_lds_dwordx4 v[156:157], off
	v_lshl_add_u64 v[156:157], v[232:233], 0, s[20:21]
	s_mov_b32 m0, s62
	s_nop 0
	global_load_lds_dwordx4 v[156:157], off
	s_waitcnt vmcnt(8)
	s_waitcnt lgkmcnt(0)
	s_barrier
	s_waitcnt lgkmcnt(0)
	v_mfma_f32_16x16x32_bf16 v[60:63], v[152:155], v[198:201], v[60:63]
	v_mfma_f32_16x16x32_bf16 v[56:59], v[170:173], v[198:201], v[56:59]
	v_mfma_f32_16x16x32_bf16 v[40:43], v[170:173], v[206:209], v[40:43]
	v_mfma_f32_16x16x32_bf16 v[44:47], v[152:155], v[206:209], v[44:47]
	v_mfma_f32_16x16x32_bf16 v[28:31], v[152:155], v[214:217], v[28:31]
	v_mfma_f32_16x16x32_bf16 v[24:27], v[170:173], v[214:217], v[24:27]
	v_mfma_f32_16x16x32_bf16 v[8:11], v[170:173], v[222:225], v[8:11]
	v_mfma_f32_16x16x32_bf16 v[12:15], v[152:155], v[222:225], v[12:15]
	v_mfma_f32_16x16x32_bf16 v[60:63], v[166:169], v[202:205], v[60:63]
	v_mfma_f32_16x16x32_bf16 v[56:59], v[174:177], v[202:205], v[56:59]
	v_mfma_f32_16x16x32_bf16 v[40:43], v[174:177], v[210:213], v[40:43]
	v_mfma_f32_16x16x32_bf16 v[44:47], v[166:169], v[210:213], v[44:47]
	v_mfma_f32_16x16x32_bf16 v[28:31], v[166:169], v[218:221], v[28:31]
	v_mfma_f32_16x16x32_bf16 v[24:27], v[174:177], v[218:221], v[24:27]
	v_mfma_f32_16x16x32_bf16 v[8:11], v[174:177], v[226:229], v[8:11]
	v_mfma_f32_16x16x32_bf16 v[12:15], v[166:169], v[226:229], v[12:15]
	v_mfma_f32_16x16x32_bf16 v[52:55], v[178:181], v[198:201], v[52:55]
	v_mfma_f32_16x16x32_bf16 v[48:51], v[186:189], v[198:201], v[48:51]
	v_mfma_f32_16x16x32_bf16 v[32:35], v[186:189], v[206:209], v[32:35]
	v_mfma_f32_16x16x32_bf16 v[36:39], v[178:181], v[206:209], v[36:39]
	v_mfma_f32_16x16x32_bf16 v[20:23], v[178:181], v[214:217], v[20:23]
	v_mfma_f32_16x16x32_bf16 v[16:19], v[186:189], v[214:217], v[16:19]
	v_mfma_f32_16x16x32_bf16 v[0:3], v[186:189], v[222:225], v[0:3]
	v_mfma_f32_16x16x32_bf16 v[4:7], v[178:181], v[222:225], v[4:7]
	v_mfma_f32_16x16x32_bf16 v[52:55], v[182:185], v[202:205], v[52:55]
	v_mfma_f32_16x16x32_bf16 v[48:51], v[194:197], v[202:205], v[48:51]
	v_mfma_f32_16x16x32_bf16 v[32:35], v[194:197], v[210:213], v[32:35]
	v_mfma_f32_16x16x32_bf16 v[36:39], v[182:185], v[210:213], v[36:39]
	v_mfma_f32_16x16x32_bf16 v[20:23], v[182:185], v[218:221], v[20:23]
	v_mfma_f32_16x16x32_bf16 v[16:19], v[194:197], v[218:221], v[16:19]
	v_mfma_f32_16x16x32_bf16 v[0:3], v[194:197], v[226:229], v[0:3]
	v_mfma_f32_16x16x32_bf16 v[4:7], v[182:185], v[226:229], v[4:7]
	s_barrier
	s_add_i32 s68, s68, 2
	s_add_u32 s38, s38, 0x100
	s_addc_u32 s39, s39, 0
	s_add_u32 s66, s66, 0x100
	s_addc_u32 s67, s67, 0
	s_cmp_gt_u32 s68, 29
	s_cbranch_scc0 .LBB0_1420
	v_lshl_add_u32 v156, s34, 8, v158
	v_lshl_or_b32 v154, s36, 8, v160
	v_ashrrev_i32_e32 v157, 31, v156
	v_ashrrev_i32_e32 v155, 31, v154
	v_lshlrev_b64 v[152:153], 11, v[156:157]
	v_lshl_add_u64 v[152:153], v[152:153], 0, v[154:155]
	v_lshlrev_b64 v[170:171], 1, v[152:153]
	v_lshl_add_u64 v[172:173], s[12:13], 0, v[170:171]
	global_load_dwordx4 v[180:183], v[172:173], off
	global_load_dwordx4 v[184:187], v[172:173], off offset:256
	v_add_co_u32_e32 v252, vcc, 0x10000, v172
	s_nop 1
	v_addc_co_u32_e32 v253, vcc, 0, v173, vcc
	global_load_dwordx4 v[188:191], v[252:253], off
	global_load_dwordx4 v[194:197], v[252:253], off offset:256
	v_add_co_u32_e32 v254, vcc, 0x20000, v172
	s_nop 1
	v_addc_co_u32_e32 v255, vcc, 0, v173, vcc
	global_load_dwordx4 v[198:201], v[254:255], off
	global_load_dwordx4 v[202:205], v[254:255], off offset:256
	v_add_co_u32_e32 v252, vcc, 0x30000, v172
	s_nop 1
	v_addc_co_u32_e32 v253, vcc, 0, v173, vcc
	global_load_dwordx4 v[206:209], v[252:253], off
	global_load_dwordx4 v[210:213], v[252:253], off offset:256
	v_add_co_u32_e32 v254, vcc, 0x80000, v172
	s_nop 1
	v_addc_co_u32_e32 v255, vcc, 0, v173, vcc
	global_load_dwordx4 v[214:217], v[254:255], off
	global_load_dwordx4 v[218:221], v[254:255], off offset:256
	v_add_co_u32_e32 v252, vcc, 0x90000, v172
	s_nop 1
	v_addc_co_u32_e32 v253, vcc, 0, v173, vcc
	global_load_dwordx4 v[222:225], v[252:253], off
	global_load_dwordx4 v[226:229], v[252:253], off offset:256
	v_add_co_u32_e32 v254, vcc, 0xa0000, v172
	s_nop 1
	v_addc_co_u32_e32 v255, vcc, 0, v173, vcc
	global_load_dwordx4 v[230:233], v[254:255], off
	global_load_dwordx4 v[234:237], v[254:255], off offset:256
	v_add_co_u32_e32 v252, vcc, 0xb0000, v172
	s_nop 1
	v_addc_co_u32_e32 v253, vcc, 0, v173, vcc
	global_load_dwordx4 v[238:241], v[252:253], off
	global_load_dwordx4 v[242:245], v[252:253], off offset:256
	s_and_b64 vcc, exec, s[22:23]
	s_cbranch_vccz .LBB0_1423
	s_barrier

.LBB0_1504:
	ds_read_b128 v[144:147], v153
	ds_read_b128 v[158:161], v153 offset:1024
	ds_read_b128 v[162:165], v153 offset:2048
	ds_read_b128 v[166:169], v153 offset:3072
	ds_read_b128 v[170:173], v154
	ds_read_b128 v[174:177], v154 offset:1024
	ds_read_b128 v[178:181], v154 offset:2048
	ds_read_b128 v[182:185], v154 offset:3072
	s_add_u32 s30, s28, 0xfff80080
	s_addc_u32 s31, s29, -1
	s_cmp_eq_u32 s65, 28
	s_cselect_b32 s35, s23, s31
	s_cselect_b32 s34, s61, s30
	s_cselect_b32 s31, s21, s64
	s_cselect_b32 s30, s62, s63
	v_lshl_add_u64 v[148:149], s[28:29], 0, v[136:137]
	s_add_i32 m0, s42, 0xc000
	ds_read_b128 v[186:189], v155
	ds_read_b128 v[194:197], v155 offset:1024
	ds_read_b128 v[198:201], v155 offset:2048
	ds_read_b128 v[202:205], v155 offset:3072
	ds_read_b128 v[206:209], v155 offset:4096
	ds_read_b128 v[210:213], v155 offset:5120
	ds_read_b128 v[214:217], v155 offset:6144
	ds_read_b128 v[218:221], v155 offset:7168
	global_load_lds_dwordx4 v[148:149], off
	v_lshl_add_u64 v[148:149], s[28:29], 0, v[138:139]
	s_add_i32 m0, s42, 0xe000
	s_nop 0
	global_load_lds_dwordx4 v[148:149], off
	s_waitcnt vmcnt(8)
	s_waitcnt lgkmcnt(0)
	s_barrier
	s_waitcnt lgkmcnt(0)
	v_mfma_f32_16x16x32_bf16 v[116:119], v[144:147], v[186:189], v[116:119]
	v_mfma_f32_16x16x32_bf16 v[112:115], v[162:165], v[186:189], v[112:115]
	v_mfma_f32_16x16x32_bf16 v[96:99], v[162:165], v[198:201], v[96:99]
	v_mfma_f32_16x16x32_bf16 v[100:103], v[144:147], v[198:201], v[100:103]
	v_mfma_f32_16x16x32_bf16 v[84:87], v[144:147], v[206:209], v[84:87]
	v_mfma_f32_16x16x32_bf16 v[80:83], v[162:165], v[206:209], v[80:83]
	v_mfma_f32_16x16x32_bf16 v[64:67], v[162:165], v[214:217], v[64:67]
	v_mfma_f32_16x16x32_bf16 v[68:71], v[144:147], v[214:217], v[68:71]
	v_mfma_f32_16x16x32_bf16 v[116:119], v[158:161], v[194:197], v[116:119]
	v_mfma_f32_16x16x32_bf16 v[112:115], v[166:169], v[194:197], v[112:115]
	v_mfma_f32_16x16x32_bf16 v[96:99], v[166:169], v[202:205], v[96:99]
	v_mfma_f32_16x16x32_bf16 v[100:103], v[158:161], v[202:205], v[100:103]
	v_mfma_f32_16x16x32_bf16 v[84:87], v[158:161], v[210:213], v[84:87]
	v_mfma_f32_16x16x32_bf16 v[80:83], v[166:169], v[210:213], v[80:83]
	v_mfma_f32_16x16x32_bf16 v[64:67], v[166:169], v[218:221], v[64:67]
	v_mfma_f32_16x16x32_bf16 v[68:71], v[158:161], v[218:221], v[68:71]
	v_mfma_f32_16x16x32_bf16 v[124:127], v[170:173], v[186:189], v[124:127]
	v_mfma_f32_16x16x32_bf16 v[120:123], v[178:181], v[186:189], v[120:123]
	v_mfma_f32_16x16x32_bf16 v[104:107], v[178:181], v[198:201], v[104:107]
	v_mfma_f32_16x16x32_bf16 v[108:111], v[170:173], v[198:201], v[108:111]
	v_mfma_f32_16x16x32_bf16 v[92:95], v[170:173], v[206:209], v[92:95]
	v_mfma_f32_16x16x32_bf16 v[88:91], v[178:181], v[206:209], v[88:91]
	v_mfma_f32_16x16x32_bf16 v[72:75], v[178:181], v[214:217], v[72:75]
	v_mfma_f32_16x16x32_bf16 v[76:79], v[170:173], v[214:217], v[76:79]
	v_mfma_f32_16x16x32_bf16 v[124:127], v[174:177], v[194:197], v[124:127]
	v_mfma_f32_16x16x32_bf16 v[120:123], v[182:185], v[194:197], v[120:123]
	v_mfma_f32_16x16x32_bf16 v[104:107], v[182:185], v[202:205], v[104:107]
	v_mfma_f32_16x16x32_bf16 v[108:111], v[174:177], v[202:205], v[108:111]
	v_mfma_f32_16x16x32_bf16 v[92:95], v[174:177], v[210:213], v[92:95]
	v_mfma_f32_16x16x32_bf16 v[88:91], v[182:185], v[210:213], v[88:91]
	v_mfma_f32_16x16x32_bf16 v[72:75], v[182:185], v[218:221], v[72:75]
	v_mfma_f32_16x16x32_bf16 v[76:79], v[174:177], v[218:221], v[76:79]
	s_barrier
	s_add_i32 s33, s57, s40
	v_lshl_add_u64 v[148:149], s[30:31], 0, v[132:133]
	s_mov_b32 m0, s33
	ds_read_b128 v[186:189], v155 offset:16384
	ds_read_b128 v[194:197], v155 offset:17408
	ds_read_b128 v[198:201], v155 offset:18432
	ds_read_b128 v[202:205], v155 offset:19456
	ds_read_b128 v[206:209], v155 offset:20480
	ds_read_b128 v[210:213], v155 offset:21504
	ds_read_b128 v[214:217], v155 offset:22528
	ds_read_b128 v[218:221], v155 offset:23552
	global_load_lds_dwordx4 v[148:149], off
	s_add_i32 m0, s33, 0x2000
	s_add_u32 s54, s30, 0x80000
	v_lshl_add_u64 v[190:191], s[30:31], 0, v[128:129]
	s_addc_u32 s55, s31, 0
	s_add_i32 s33, s58, s40
	global_load_lds_dwordx4 v[190:191], off
	v_lshl_add_u64 v[222:223], s[54:55], 0, v[132:133]
	s_mov_b32 m0, s33
	v_lshl_add_u64 v[224:225], s[34:35], 0, v[130:131]
	global_load_lds_dwordx4 v[222:223], off
	v_lshl_add_u64 v[222:223], s[54:55], 0, v[128:129]
	s_add_i32 m0, s33, 0x2000
	s_nop 0
	global_load_lds_dwordx4 v[222:223], off
	v_lshl_add_u64 v[222:223], s[34:35], 0, v[134:135]
	s_mov_b32 m0, s42
	s_nop 0
	global_load_lds_dwordx4 v[222:223], off
	s_mov_b32 m0, s43
	s_nop 0
	global_load_lds_dwordx4 v[224:225], off
	s_waitcnt vmcnt(8)
	s_waitcnt lgkmcnt(0)
	s_barrier
	s_waitcnt lgkmcnt(0)
	v_mfma_f32_16x16x32_bf16 v[52:55], v[144:147], v[186:189], v[52:55]
	v_mfma_f32_16x16x32_bf16 v[48:51], v[162:165], v[186:189], v[48:51]
	v_mfma_f32_16x16x32_bf16 v[32:35], v[162:165], v[198:201], v[32:35]
	v_mfma_f32_16x16x32_bf16 v[36:39], v[144:147], v[198:201], v[36:39]
	v_mfma_f32_16x16x32_bf16 v[20:23], v[144:147], v[206:209], v[20:23]
	v_mfma_f32_16x16x32_bf16 v[16:19], v[162:165], v[206:209], v[16:19]
	v_mfma_f32_16x16x32_bf16 v[0:3], v[162:165], v[214:217], v[0:3]
	v_mfma_f32_16x16x32_bf16 v[4:7], v[144:147], v[214:217], v[4:7]
	v_mfma_f32_16x16x32_bf16 v[52:55], v[158:161], v[194:197], v[52:55]
	v_mfma_f32_16x16x32_bf16 v[48:51], v[166:169], v[194:197], v[48:51]
	v_mfma_f32_16x16x32_bf16 v[32:35], v[166:169], v[202:205], v[32:35]
	v_mfma_f32_16x16x32_bf16 v[36:39], v[158:161], v[202:205], v[36:39]
	v_mfma_f32_16x16x32_bf16 v[20:23], v[158:161], v[210:213], v[20:23]
	v_mfma_f32_16x16x32_bf16 v[16:19], v[166:169], v[210:213], v[16:19]
	v_mfma_f32_16x16x32_bf16 v[0:3], v[166:169], v[218:221], v[0:3]
	v_mfma_f32_16x16x32_bf16 v[4:7], v[158:161], v[218:221], v[4:7]
	v_mfma_f32_16x16x32_bf16 v[60:63], v[170:173], v[186:189], v[60:63]
	v_mfma_f32_16x16x32_bf16 v[56:59], v[178:181], v[186:189], v[56:59]
	v_mfma_f32_16x16x32_bf16 v[40:43], v[178:181], v[198:201], v[40:43]
	v_mfma_f32_16x16x32_bf16 v[44:47], v[170:173], v[198:201], v[44:47]
	v_mfma_f32_16x16x32_bf16 v[28:31], v[170:173], v[206:209], v[28:31]
	v_mfma_f32_16x16x32_bf16 v[24:27], v[178:181], v[206:209], v[24:27]
	v_mfma_f32_16x16x32_bf16 v[8:11], v[178:181], v[214:217], v[8:11]
	v_mfma_f32_16x16x32_bf16 v[12:15], v[170:173], v[214:217], v[12:15]
	v_mfma_f32_16x16x32_bf16 v[60:63], v[174:177], v[194:197], v[60:63]
	v_mfma_f32_16x16x32_bf16 v[56:59], v[182:185], v[194:197], v[56:59]
	v_mfma_f32_16x16x32_bf16 v[40:43], v[182:185], v[202:205], v[40:43]
	v_mfma_f32_16x16x32_bf16 v[44:47], v[174:177], v[202:205], v[44:47]
	v_mfma_f32_16x16x32_bf16 v[28:31], v[174:177], v[210:213], v[28:31]
	v_mfma_f32_16x16x32_bf16 v[24:27], v[182:185], v[210:213], v[24:27]
	v_mfma_f32_16x16x32_bf16 v[8:11], v[182:185], v[218:221], v[8:11]
	v_mfma_f32_16x16x32_bf16 v[12:15], v[174:177], v[218:221], v[12:15]
	s_barrier
	s_add_i32 s33, 0, 0x18000
	s_add_i32 s54, 0, 0x1c000
	v_add_u32_e32 v166, s33, v151
	v_add_u32_e32 v182, s54, v151
	ds_read_b128 v[144:147], v166
	ds_read_b128 v[158:161], v166 offset:1024
	ds_read_b128 v[162:165], v166 offset:2048
	ds_read_b128 v[166:169], v166 offset:3072
	ds_read_b128 v[170:173], v182
	ds_read_b128 v[174:177], v182 offset:1024
	ds_read_b128 v[178:181], v182 offset:2048
	ds_read_b128 v[182:185], v182 offset:3072
	s_add_u32 s34, s34, 0x80000
	s_addc_u32 s35, s35, 0
	s_mov_b32 m0, s48
	v_lshl_add_u64 v[226:227], s[34:35], 0, v[134:135]
	ds_read_b128 v[186:189], v155 offset:32768
	ds_read_b128 v[194:197], v155 offset:33792
	ds_read_b128 v[198:201], v155 offset:34816
	ds_read_b128 v[202:205], v155 offset:35840
	ds_read_b128 v[206:209], v155 offset:36864
	ds_read_b128 v[210:213], v155 offset:37888
	ds_read_b128 v[214:217], v155 offset:38912
	ds_read_b128 v[218:221], v155 offset:39936
	global_load_lds_dwordx4 v[226:227], off
	v_lshl_add_u64 v[226:227], s[34:35], 0, v[130:131]
	s_mov_b32 m0, s49
	s_nop 0
	global_load_lds_dwordx4 v[226:227], off
	s_waitcnt vmcnt(8)
	s_waitcnt lgkmcnt(0)
	s_barrier
	s_waitcnt lgkmcnt(0)
	v_mfma_f32_16x16x32_bf16 v[116:119], v[144:147], v[186:189], v[116:119]
	v_mfma_f32_16x16x32_bf16 v[112:115], v[162:165], v[186:189], v[112:115]
	v_mfma_f32_16x16x32_bf16 v[96:99], v[162:165], v[198:201], v[96:99]
	v_mfma_f32_16x16x32_bf16 v[100:103], v[144:147], v[198:201], v[100:103]
	v_mfma_f32_16x16x32_bf16 v[84:87], v[144:147], v[206:209], v[84:87]
	v_mfma_f32_16x16x32_bf16 v[80:83], v[162:165], v[206:209], v[80:83]
	v_mfma_f32_16x16x32_bf16 v[64:67], v[162:165], v[214:217], v[64:67]
	v_mfma_f32_16x16x32_bf16 v[68:71], v[144:147], v[214:217], v[68:71]
	v_mfma_f32_16x16x32_bf16 v[116:119], v[158:161], v[194:197], v[116:119]
	v_mfma_f32_16x16x32_bf16 v[112:115], v[166:169], v[194:197], v[112:115]
	v_mfma_f32_16x16x32_bf16 v[96:99], v[166:169], v[202:205], v[96:99]
	v_mfma_f32_16x16x32_bf16 v[100:103], v[158:161], v[202:205], v[100:103]
	v_mfma_f32_16x16x32_bf16 v[84:87], v[158:161], v[210:213], v[84:87]
	v_mfma_f32_16x16x32_bf16 v[80:83], v[166:169], v[210:213], v[80:83]
	v_mfma_f32_16x16x32_bf16 v[64:67], v[166:169], v[218:221], v[64:67]
	v_mfma_f32_16x16x32_bf16 v[68:71], v[158:161], v[218:221], v[68:71]
	v_mfma_f32_16x16x32_bf16 v[124:127], v[170:173], v[186:189], v[124:127]
	v_mfma_f32_16x16x32_bf16 v[120:123], v[178:181], v[186:189], v[120:123]
	v_mfma_f32_16x16x32_bf16 v[104:107], v[178:181], v[198:201], v[104:107]
	v_mfma_f32_16x16x32_bf16 v[108:111], v[170:173], v[198:201], v[108:111]
	v_mfma_f32_16x16x32_bf16 v[92:95], v[170:173], v[206:209], v[92:95]
	v_mfma_f32_16x16x32_bf16 v[88:91], v[178:181], v[206:209], v[88:91]
	v_mfma_f32_16x16x32_bf16 v[72:75], v[178:181], v[214:217], v[72:75]
	v_mfma_f32_16x16x32_bf16 v[76:79], v[170:173], v[214:217], v[76:79]
	v_mfma_f32_16x16x32_bf16 v[124:127], v[174:177], v[194:197], v[124:127]
	v_mfma_f32_16x16x32_bf16 v[120:123], v[182:185], v[194:197], v[120:123]
	v_mfma_f32_16x16x32_bf16 v[104:107], v[182:185], v[202:205], v[104:107]
	v_mfma_f32_16x16x32_bf16 v[108:111], v[174:177], v[202:205], v[108:111]
	v_mfma_f32_16x16x32_bf16 v[92:95], v[174:177], v[210:213], v[92:95]
	v_mfma_f32_16x16x32_bf16 v[88:91], v[182:185], v[210:213], v[88:91]
	v_mfma_f32_16x16x32_bf16 v[72:75], v[182:185], v[218:221], v[72:75]
	v_mfma_f32_16x16x32_bf16 v[76:79], v[174:177], v[218:221], v[76:79]
	s_barrier
	s_add_i32 s33, s33, s40
	v_lshl_add_u64 v[148:149], v[148:149], 0, s[16:17]
	s_mov_b32 m0, s33
	ds_read_b128 v[186:189], v155 offset:49152
	ds_read_b128 v[194:197], v155 offset:50176
	ds_read_b128 v[198:201], v155 offset:51200
	ds_read_b128 v[202:205], v155 offset:52224
	ds_read_b128 v[206:209], v155 offset:53248
	ds_read_b128 v[210:213], v155 offset:54272
	ds_read_b128 v[214:217], v155 offset:55296
	ds_read_b128 v[218:221], v155 offset:56320
	global_load_lds_dwordx4 v[148:149], off
	s_add_i32 m0, s33, 0x2000
	s_add_u32 s30, s30, 0x80080
	v_lshl_add_u64 v[148:149], v[190:191], 0, s[16:17]
	s_addc_u32 s31, s31, 0
	s_add_i32 s33, s54, s40
	global_load_lds_dwordx4 v[148:149], off
	v_lshl_add_u64 v[148:149], s[30:31], 0, v[132:133]
	s_mov_b32 m0, s33
	s_nop 0
	global_load_lds_dwordx4 v[148:149], off
	v_lshl_add_u64 v[148:149], s[30:31], 0, v[128:129]
	s_add_i32 m0, s33, 0x2000
	s_nop 0
	global_load_lds_dwordx4 v[148:149], off
	v_lshl_add_u64 v[148:149], v[222:223], 0, s[16:17]
	s_mov_b32 m0, s51
	s_nop 0
	global_load_lds_dwordx4 v[148:149], off
	v_lshl_add_u64 v[148:149], v[224:225], 0, s[16:17]
	s_mov_b32 m0, s56
	s_nop 0
	global_load_lds_dwordx4 v[148:149], off
	s_waitcnt vmcnt(8)
	s_waitcnt lgkmcnt(0)
	s_barrier
	s_waitcnt lgkmcnt(0)
	v_mfma_f32_16x16x32_bf16 v[52:55], v[144:147], v[186:189], v[52:55]
	v_mfma_f32_16x16x32_bf16 v[48:51], v[162:165], v[186:189], v[48:51]
	v_mfma_f32_16x16x32_bf16 v[32:35], v[162:165], v[198:201], v[32:35]
	v_mfma_f32_16x16x32_bf16 v[36:39], v[144:147], v[198:201], v[36:39]
	v_mfma_f32_16x16x32_bf16 v[20:23], v[144:147], v[206:209], v[20:23]
	v_mfma_f32_16x16x32_bf16 v[16:19], v[162:165], v[206:209], v[16:19]
	v_mfma_f32_16x16x32_bf16 v[0:3], v[162:165], v[214:217], v[0:3]
	v_mfma_f32_16x16x32_bf16 v[4:7], v[144:147], v[214:217], v[4:7]
	v_mfma_f32_16x16x32_bf16 v[52:55], v[158:161], v[194:197], v[52:55]
	v_mfma_f32_16x16x32_bf16 v[48:51], v[166:169], v[194:197], v[48:51]
	v_mfma_f32_16x16x32_bf16 v[32:35], v[166:169], v[202:205], v[32:35]
	v_mfma_f32_16x16x32_bf16 v[36:39], v[158:161], v[202:205], v[36:39]
	v_mfma_f32_16x16x32_bf16 v[20:23], v[158:161], v[210:213], v[20:23]
	v_mfma_f32_16x16x32_bf16 v[16:19], v[166:169], v[210:213], v[16:19]
	v_mfma_f32_16x16x32_bf16 v[0:3], v[166:169], v[218:221], v[0:3]
	v_mfma_f32_16x16x32_bf16 v[4:7], v[158:161], v[218:221], v[4:7]
	v_mfma_f32_16x16x32_bf16 v[60:63], v[170:173], v[186:189], v[60:63]
	v_mfma_f32_16x16x32_bf16 v[56:59], v[178:181], v[186:189], v[56:59]
	v_mfma_f32_16x16x32_bf16 v[40:43], v[178:181], v[198:201], v[40:43]
	v_mfma_f32_16x16x32_bf16 v[44:47], v[170:173], v[198:201], v[44:47]
	v_mfma_f32_16x16x32_bf16 v[28:31], v[170:173], v[206:209], v[28:31]
	v_mfma_f32_16x16x32_bf16 v[24:27], v[178:181], v[206:209], v[24:27]
	v_mfma_f32_16x16x32_bf16 v[8:11], v[178:181], v[214:217], v[8:11]
	v_mfma_f32_16x16x32_bf16 v[12:15], v[170:173], v[214:217], v[12:15]
	v_mfma_f32_16x16x32_bf16 v[60:63], v[174:177], v[194:197], v[60:63]
	v_mfma_f32_16x16x32_bf16 v[56:59], v[182:185], v[194:197], v[56:59]
	v_mfma_f32_16x16x32_bf16 v[40:43], v[182:185], v[202:205], v[40:43]
	v_mfma_f32_16x16x32_bf16 v[44:47], v[174:177], v[202:205], v[44:47]
	v_mfma_f32_16x16x32_bf16 v[28:31], v[174:177], v[210:213], v[28:31]
	v_mfma_f32_16x16x32_bf16 v[24:27], v[182:185], v[210:213], v[24:27]
	v_mfma_f32_16x16x32_bf16 v[8:11], v[182:185], v[218:221], v[8:11]
	v_mfma_f32_16x16x32_bf16 v[12:15], v[174:177], v[218:221], v[12:15]
	s_barrier
	s_add_i32 s65, s65, 2
	s_add_u32 s28, s28, 0x100
	s_addc_u32 s29, s29, 0
	s_add_u32 s63, s63, 0x100
	s_addc_u32 s64, s64, 0
	s_cmp_gt_u32 s65, 29
	s_cbranch_scc0 .LBB0_1504
	v_lshl_add_u32 v144, s8, 8, v150
	v_ashrrev_i32_e32 v145, 31, v144
	v_lshl_add_u64 v[148:149], v[144:145], 2, s[14:15]
	global_load_dword v172, v[148:149], off
	global_load_dword v173, v[148:149], off offset:64
	global_load_dword v174, v[148:149], off offset:128
	global_load_dword v175, v[148:149], off offset:192
	global_load_dword v176, v[148:149], off offset:512
	global_load_dword v177, v[148:149], off offset:576
	global_load_dword v178, v[148:149], off offset:640
	global_load_dword v179, v[148:149], off offset:704
	s_and_b64 vcc, exec, s[18:19]
	s_cbranch_vccz .LBB0_1507
	s_barrier

.LBB0_2011:
	ds_read_b128 v[144:147], v153
	ds_read_b128 v[158:161], v153 offset:1024
	ds_read_b128 v[162:165], v153 offset:2048
	ds_read_b128 v[166:169], v153 offset:3072
	ds_read_b128 v[170:173], v154
	ds_read_b128 v[174:177], v154 offset:1024
	ds_read_b128 v[178:181], v154 offset:2048
	ds_read_b128 v[182:185], v154 offset:3072
	s_add_u32 s36, s34, 0x100
	s_addc_u32 s37, s35, 0
	s_cmpk_eq_i32 s68, 0x54
	s_cselect_b32 s41, s11, s37
	s_cselect_b32 s40, s10, s36
	s_cselect_b32 s39, s31, s67
	s_cselect_b32 s38, s30, s66
	v_lshl_add_u64 v[148:149], s[34:35], 0, v[136:137]
	s_add_i32 m0, s51, 0xc000
	ds_read_b128 v[186:189], v155
	ds_read_b128 v[194:197], v155 offset:1024
	ds_read_b128 v[198:201], v155 offset:2048
	ds_read_b128 v[202:205], v155 offset:3072
	ds_read_b128 v[206:209], v155 offset:4096
	ds_read_b128 v[210:213], v155 offset:5120
	ds_read_b128 v[214:217], v155 offset:6144
	ds_read_b128 v[218:221], v155 offset:7168
	global_load_lds_dwordx4 v[148:149], off
	v_lshl_add_u64 v[148:149], s[34:35], 0, v[138:139]
	s_add_i32 m0, s51, 0xe000
	s_nop 0
	global_load_lds_dwordx4 v[148:149], off
	s_waitcnt vmcnt(8)
	s_waitcnt lgkmcnt(0)
	s_barrier
	s_waitcnt lgkmcnt(0)
	v_mfma_f32_16x16x32_bf16 v[124:127], v[144:147], v[186:189], v[124:127]
	v_mfma_f32_16x16x32_bf16 v[120:123], v[162:165], v[186:189], v[120:123]
	v_mfma_f32_16x16x32_bf16 v[104:107], v[162:165], v[198:201], v[104:107]
	v_mfma_f32_16x16x32_bf16 v[108:111], v[144:147], v[198:201], v[108:111]
	v_mfma_f32_16x16x32_bf16 v[92:95], v[144:147], v[206:209], v[92:95]
	v_mfma_f32_16x16x32_bf16 v[88:91], v[162:165], v[206:209], v[88:91]
	v_mfma_f32_16x16x32_bf16 v[72:75], v[162:165], v[214:217], v[72:75]
	v_mfma_f32_16x16x32_bf16 v[76:79], v[144:147], v[214:217], v[76:79]
	v_mfma_f32_16x16x32_bf16 v[124:127], v[158:161], v[194:197], v[124:127]
	v_mfma_f32_16x16x32_bf16 v[120:123], v[166:169], v[194:197], v[120:123]
	v_mfma_f32_16x16x32_bf16 v[104:107], v[166:169], v[202:205], v[104:107]
	v_mfma_f32_16x16x32_bf16 v[108:111], v[158:161], v[202:205], v[108:111]
	v_mfma_f32_16x16x32_bf16 v[92:95], v[158:161], v[210:213], v[92:95]
	v_mfma_f32_16x16x32_bf16 v[88:91], v[166:169], v[210:213], v[88:91]
	v_mfma_f32_16x16x32_bf16 v[72:75], v[166:169], v[218:221], v[72:75]
	v_mfma_f32_16x16x32_bf16 v[76:79], v[158:161], v[218:221], v[76:79]
	v_mfma_f32_16x16x32_bf16 v[116:119], v[170:173], v[186:189], v[116:119]
	v_mfma_f32_16x16x32_bf16 v[112:115], v[178:181], v[186:189], v[112:115]
	v_mfma_f32_16x16x32_bf16 v[96:99], v[178:181], v[198:201], v[96:99]
	v_mfma_f32_16x16x32_bf16 v[100:103], v[170:173], v[198:201], v[100:103]
	v_mfma_f32_16x16x32_bf16 v[84:87], v[170:173], v[206:209], v[84:87]
	v_mfma_f32_16x16x32_bf16 v[80:83], v[178:181], v[206:209], v[80:83]
	v_mfma_f32_16x16x32_bf16 v[64:67], v[178:181], v[214:217], v[64:67]
	v_mfma_f32_16x16x32_bf16 v[68:71], v[170:173], v[214:217], v[68:71]
	v_mfma_f32_16x16x32_bf16 v[116:119], v[174:177], v[194:197], v[116:119]
	v_mfma_f32_16x16x32_bf16 v[112:115], v[182:185], v[194:197], v[112:115]
	v_mfma_f32_16x16x32_bf16 v[96:99], v[182:185], v[202:205], v[96:99]
	v_mfma_f32_16x16x32_bf16 v[100:103], v[174:177], v[202:205], v[100:103]
	v_mfma_f32_16x16x32_bf16 v[84:87], v[174:177], v[210:213], v[84:87]
	v_mfma_f32_16x16x32_bf16 v[80:83], v[182:185], v[210:213], v[80:83]
	v_mfma_f32_16x16x32_bf16 v[64:67], v[182:185], v[218:221], v[64:67]
	v_mfma_f32_16x16x32_bf16 v[68:71], v[174:177], v[218:221], v[68:71]
	s_barrier
	s_add_i32 s33, s60, s50
	v_lshl_add_u64 v[148:149], s[38:39], 0, v[130:131]
	s_mov_b32 m0, s33
	ds_read_b128 v[186:189], v155 offset:16384
	ds_read_b128 v[194:197], v155 offset:17408
	ds_read_b128 v[198:201], v155 offset:18432
	ds_read_b128 v[202:205], v155 offset:19456
	ds_read_b128 v[206:209], v155 offset:20480
	ds_read_b128 v[210:213], v155 offset:21504
	ds_read_b128 v[214:217], v155 offset:22528
	ds_read_b128 v[218:221], v155 offset:23552
	global_load_lds_dwordx4 v[148:149], off
	s_add_i32 m0, s33, 0x2000
	s_add_u32 s34, s38, 0x160000
	v_lshl_add_u64 v[190:191], s[38:39], 0, v[134:135]
	s_addc_u32 s35, s39, 0
	s_add_i32 s33, s61, s50
	global_load_lds_dwordx4 v[190:191], off
	v_lshl_add_u64 v[222:223], s[34:35], 0, v[130:131]
	s_mov_b32 m0, s33
	v_lshl_add_u64 v[224:225], s[40:41], 0, v[132:133]
	global_load_lds_dwordx4 v[222:223], off
	v_lshl_add_u64 v[222:223], s[34:35], 0, v[134:135]
	s_add_i32 m0, s33, 0x2000
	s_nop 0
	global_load_lds_dwordx4 v[222:223], off
	v_lshl_add_u64 v[222:223], s[40:41], 0, v[128:129]
	s_mov_b32 m0, s51
	s_nop 0
	global_load_lds_dwordx4 v[222:223], off
	s_mov_b32 m0, s54
	s_nop 0
	global_load_lds_dwordx4 v[224:225], off
	s_waitcnt vmcnt(8)
	s_waitcnt lgkmcnt(0)
	s_barrier
	s_waitcnt lgkmcnt(0)
	v_mfma_f32_16x16x32_bf16 v[60:63], v[144:147], v[186:189], v[60:63]
	v_mfma_f32_16x16x32_bf16 v[56:59], v[162:165], v[186:189], v[56:59]
	v_mfma_f32_16x16x32_bf16 v[40:43], v[162:165], v[198:201], v[40:43]
	v_mfma_f32_16x16x32_bf16 v[44:47], v[144:147], v[198:201], v[44:47]
	v_mfma_f32_16x16x32_bf16 v[28:31], v[144:147], v[206:209], v[28:31]
	v_mfma_f32_16x16x32_bf16 v[24:27], v[162:165], v[206:209], v[24:27]
	v_mfma_f32_16x16x32_bf16 v[8:11], v[162:165], v[214:217], v[8:11]
	v_mfma_f32_16x16x32_bf16 v[12:15], v[144:147], v[214:217], v[12:15]
	v_mfma_f32_16x16x32_bf16 v[60:63], v[158:161], v[194:197], v[60:63]
	v_mfma_f32_16x16x32_bf16 v[56:59], v[166:169], v[194:197], v[56:59]
	v_mfma_f32_16x16x32_bf16 v[40:43], v[166:169], v[202:205], v[40:43]
	v_mfma_f32_16x16x32_bf16 v[44:47], v[158:161], v[202:205], v[44:47]
	v_mfma_f32_16x16x32_bf16 v[28:31], v[158:161], v[210:213], v[28:31]
	v_mfma_f32_16x16x32_bf16 v[24:27], v[166:169], v[210:213], v[24:27]
	v_mfma_f32_16x16x32_bf16 v[8:11], v[166:169], v[218:221], v[8:11]
	v_mfma_f32_16x16x32_bf16 v[12:15], v[158:161], v[218:221], v[12:15]
	v_mfma_f32_16x16x32_bf16 v[52:55], v[170:173], v[186:189], v[52:55]
	v_mfma_f32_16x16x32_bf16 v[48:51], v[178:181], v[186:189], v[48:51]
	v_mfma_f32_16x16x32_bf16 v[32:35], v[178:181], v[198:201], v[32:35]
	v_mfma_f32_16x16x32_bf16 v[36:39], v[170:173], v[198:201], v[36:39]
	v_mfma_f32_16x16x32_bf16 v[20:23], v[170:173], v[206:209], v[20:23]
	v_mfma_f32_16x16x32_bf16 v[16:19], v[178:181], v[206:209], v[16:19]
	v_mfma_f32_16x16x32_bf16 v[0:3], v[178:181], v[214:217], v[0:3]
	v_mfma_f32_16x16x32_bf16 v[4:7], v[170:173], v[214:217], v[4:7]
	v_mfma_f32_16x16x32_bf16 v[52:55], v[174:177], v[194:197], v[52:55]
	v_mfma_f32_16x16x32_bf16 v[48:51], v[182:185], v[194:197], v[48:51]
	v_mfma_f32_16x16x32_bf16 v[32:35], v[182:185], v[202:205], v[32:35]
	v_mfma_f32_16x16x32_bf16 v[36:39], v[174:177], v[202:205], v[36:39]
	v_mfma_f32_16x16x32_bf16 v[20:23], v[174:177], v[210:213], v[20:23]
	v_mfma_f32_16x16x32_bf16 v[16:19], v[182:185], v[210:213], v[16:19]
	v_mfma_f32_16x16x32_bf16 v[0:3], v[182:185], v[218:221], v[0:3]
	v_mfma_f32_16x16x32_bf16 v[4:7], v[174:177], v[218:221], v[4:7]
	s_barrier
	s_add_i32 s33, 0, 0x18000
	v_add_u32_e32 v157, s33, v151
	s_add_i32 s69, 0, 0x1c000
	ds_read_b128 v[144:147], v157
	ds_read_b128 v[158:161], v157 offset:1024
	ds_read_b128 v[162:165], v157 offset:2048
	ds_read_b128 v[166:169], v157 offset:3072
	v_add_u32_e32 v157, s69, v151
	ds_read_b128 v[170:173], v157
	ds_read_b128 v[174:177], v157 offset:1024
	ds_read_b128 v[178:181], v157 offset:2048
	ds_read_b128 v[182:185], v157 offset:3072
	s_add_u32 s34, s40, 0x160000
	s_addc_u32 s35, s41, 0
	s_mov_b32 m0, s55
	v_lshl_add_u64 v[226:227], s[34:35], 0, v[128:129]
	ds_read_b128 v[186:189], v155 offset:32768
	ds_read_b128 v[194:197], v155 offset:33792
	ds_read_b128 v[198:201], v155 offset:34816
	ds_read_b128 v[202:205], v155 offset:35840
	ds_read_b128 v[206:209], v155 offset:36864
	ds_read_b128 v[210:213], v155 offset:37888
	ds_read_b128 v[214:217], v155 offset:38912
	ds_read_b128 v[218:221], v155 offset:39936
	global_load_lds_dwordx4 v[226:227], off
	v_lshl_add_u64 v[226:227], s[34:35], 0, v[132:133]
	s_mov_b32 m0, s56
	s_nop 0
	global_load_lds_dwordx4 v[226:227], off
	s_waitcnt vmcnt(8)
	s_waitcnt lgkmcnt(0)
	s_barrier
	s_waitcnt lgkmcnt(0)
	v_mfma_f32_16x16x32_bf16 v[124:127], v[144:147], v[186:189], v[124:127]
	v_mfma_f32_16x16x32_bf16 v[120:123], v[162:165], v[186:189], v[120:123]
	v_mfma_f32_16x16x32_bf16 v[104:107], v[162:165], v[198:201], v[104:107]
	v_mfma_f32_16x16x32_bf16 v[108:111], v[144:147], v[198:201], v[108:111]
	v_mfma_f32_16x16x32_bf16 v[92:95], v[144:147], v[206:209], v[92:95]
	v_mfma_f32_16x16x32_bf16 v[88:91], v[162:165], v[206:209], v[88:91]
	v_mfma_f32_16x16x32_bf16 v[72:75], v[162:165], v[214:217], v[72:75]
	v_mfma_f32_16x16x32_bf16 v[76:79], v[144:147], v[214:217], v[76:79]
	v_mfma_f32_16x16x32_bf16 v[124:127], v[158:161], v[194:197], v[124:127]
	v_mfma_f32_16x16x32_bf16 v[120:123], v[166:169], v[194:197], v[120:123]
	v_mfma_f32_16x16x32_bf16 v[104:107], v[166:169], v[202:205], v[104:107]
	v_mfma_f32_16x16x32_bf16 v[108:111], v[158:161], v[202:205], v[108:111]
	v_mfma_f32_16x16x32_bf16 v[92:95], v[158:161], v[210:213], v[92:95]
	v_mfma_f32_16x16x32_bf16 v[88:91], v[166:169], v[210:213], v[88:91]
	v_mfma_f32_16x16x32_bf16 v[72:75], v[166:169], v[218:221], v[72:75]
	v_mfma_f32_16x16x32_bf16 v[76:79], v[158:161], v[218:221], v[76:79]
	v_mfma_f32_16x16x32_bf16 v[116:119], v[170:173], v[186:189], v[116:119]
	v_mfma_f32_16x16x32_bf16 v[112:115], v[178:181], v[186:189], v[112:115]
	v_mfma_f32_16x16x32_bf16 v[96:99], v[178:181], v[198:201], v[96:99]
	v_mfma_f32_16x16x32_bf16 v[100:103], v[170:173], v[198:201], v[100:103]
	v_mfma_f32_16x16x32_bf16 v[84:87], v[170:173], v[206:209], v[84:87]
	v_mfma_f32_16x16x32_bf16 v[80:83], v[178:181], v[206:209], v[80:83]
	v_mfma_f32_16x16x32_bf16 v[64:67], v[178:181], v[214:217], v[64:67]
	v_mfma_f32_16x16x32_bf16 v[68:71], v[170:173], v[214:217], v[68:71]
	v_mfma_f32_16x16x32_bf16 v[116:119], v[174:177], v[194:197], v[116:119]
	v_mfma_f32_16x16x32_bf16 v[112:115], v[182:185], v[194:197], v[112:115]
	v_mfma_f32_16x16x32_bf16 v[96:99], v[182:185], v[202:205], v[96:99]
	v_mfma_f32_16x16x32_bf16 v[100:103], v[174:177], v[202:205], v[100:103]
	v_mfma_f32_16x16x32_bf16 v[84:87], v[174:177], v[210:213], v[84:87]
	v_mfma_f32_16x16x32_bf16 v[80:83], v[182:185], v[210:213], v[80:83]
	v_mfma_f32_16x16x32_bf16 v[64:67], v[182:185], v[218:221], v[64:67]
	v_mfma_f32_16x16x32_bf16 v[68:71], v[174:177], v[218:221], v[68:71]
	s_barrier
	s_add_i32 s33, s33, s50
	v_lshl_add_u64 v[148:149], v[148:149], 0, s[18:19]
	s_mov_b32 m0, s33
	ds_read_b128 v[186:189], v155 offset:49152
	ds_read_b128 v[194:197], v155 offset:50176
	ds_read_b128 v[198:201], v155 offset:51200
	ds_read_b128 v[202:205], v155 offset:52224
	ds_read_b128 v[206:209], v155 offset:53248
	ds_read_b128 v[210:213], v155 offset:54272
	ds_read_b128 v[214:217], v155 offset:55296
	ds_read_b128 v[218:221], v155 offset:56320
	global_load_lds_dwordx4 v[148:149], off
	s_add_i32 m0, s33, 0x2000
	s_add_u32 s34, s38, 0x160080
	v_lshl_add_u64 v[148:149], v[190:191], 0, s[18:19]
	s_addc_u32 s35, s39, 0
	s_add_i32 s33, s69, s50
	global_load_lds_dwordx4 v[148:149], off
	v_lshl_add_u64 v[148:149], s[34:35], 0, v[130:131]
	s_mov_b32 m0, s33
	s_nop 0
	global_load_lds_dwordx4 v[148:149], off
	v_lshl_add_u64 v[148:149], s[34:35], 0, v[134:135]
	s_add_i32 m0, s33, 0x2000
	s_nop 0
	global_load_lds_dwordx4 v[148:149], off
	v_lshl_add_u64 v[148:149], v[222:223], 0, s[18:19]
	s_mov_b32 m0, s58
	s_nop 0
	global_load_lds_dwordx4 v[148:149], off
	v_lshl_add_u64 v[148:149], v[224:225], 0, s[18:19]
	s_mov_b32 m0, s59
	s_nop 0
	global_load_lds_dwordx4 v[148:149], off
	s_waitcnt vmcnt(8)
	s_waitcnt lgkmcnt(0)
	s_barrier
	s_waitcnt lgkmcnt(0)
	v_mfma_f32_16x16x32_bf16 v[60:63], v[144:147], v[186:189], v[60:63]
	v_mfma_f32_16x16x32_bf16 v[56:59], v[162:165], v[186:189], v[56:59]
	v_mfma_f32_16x16x32_bf16 v[40:43], v[162:165], v[198:201], v[40:43]
	v_mfma_f32_16x16x32_bf16 v[44:47], v[144:147], v[198:201], v[44:47]
	v_mfma_f32_16x16x32_bf16 v[28:31], v[144:147], v[206:209], v[28:31]
	v_mfma_f32_16x16x32_bf16 v[24:27], v[162:165], v[206:209], v[24:27]
	v_mfma_f32_16x16x32_bf16 v[8:11], v[162:165], v[214:217], v[8:11]
	v_mfma_f32_16x16x32_bf16 v[12:15], v[144:147], v[214:217], v[12:15]
	v_mfma_f32_16x16x32_bf16 v[60:63], v[158:161], v[194:197], v[60:63]
	v_mfma_f32_16x16x32_bf16 v[56:59], v[166:169], v[194:197], v[56:59]
	v_mfma_f32_16x16x32_bf16 v[40:43], v[166:169], v[202:205], v[40:43]
	v_mfma_f32_16x16x32_bf16 v[44:47], v[158:161], v[202:205], v[44:47]
	v_mfma_f32_16x16x32_bf16 v[28:31], v[158:161], v[210:213], v[28:31]
	v_mfma_f32_16x16x32_bf16 v[24:27], v[166:169], v[210:213], v[24:27]
	v_mfma_f32_16x16x32_bf16 v[8:11], v[166:169], v[218:221], v[8:11]
	v_mfma_f32_16x16x32_bf16 v[12:15], v[158:161], v[218:221], v[12:15]
	v_mfma_f32_16x16x32_bf16 v[52:55], v[170:173], v[186:189], v[52:55]
	v_mfma_f32_16x16x32_bf16 v[48:51], v[178:181], v[186:189], v[48:51]
	v_mfma_f32_16x16x32_bf16 v[32:35], v[178:181], v[198:201], v[32:35]
	v_mfma_f32_16x16x32_bf16 v[36:39], v[170:173], v[198:201], v[36:39]
	v_mfma_f32_16x16x32_bf16 v[20:23], v[170:173], v[206:209], v[20:23]
	v_mfma_f32_16x16x32_bf16 v[16:19], v[178:181], v[206:209], v[16:19]
	v_mfma_f32_16x16x32_bf16 v[0:3], v[178:181], v[214:217], v[0:3]
	v_mfma_f32_16x16x32_bf16 v[4:7], v[170:173], v[214:217], v[4:7]
	v_mfma_f32_16x16x32_bf16 v[52:55], v[174:177], v[194:197], v[52:55]
	v_mfma_f32_16x16x32_bf16 v[48:51], v[182:185], v[194:197], v[48:51]
	v_mfma_f32_16x16x32_bf16 v[32:35], v[182:185], v[202:205], v[32:35]
	v_mfma_f32_16x16x32_bf16 v[36:39], v[174:177], v[202:205], v[36:39]
	v_mfma_f32_16x16x32_bf16 v[20:23], v[174:177], v[210:213], v[20:23]
	v_mfma_f32_16x16x32_bf16 v[16:19], v[182:185], v[210:213], v[16:19]
	v_mfma_f32_16x16x32_bf16 v[0:3], v[182:185], v[218:221], v[0:3]
	v_mfma_f32_16x16x32_bf16 v[4:7], v[174:177], v[218:221], v[4:7]
	s_barrier
	s_add_i32 s68, s68, 2
	s_add_u32 s66, s66, 0x100
	s_addc_u32 s67, s67, 0
	s_cmpk_gt_u32 s68, 0x55
	s_mov_b64 s[34:35], s[36:37]
	s_cbranch_scc0 .LBB0_2011
	s_and_b64 vcc, exec, s[20:21]
	s_cbranch_vccz .LBB0_2014
	s_barrier

.LBB0_2113:
	v_add_u32_e32 v151, s48, v149
	ds_read_b128 v[152:155], v151
	ds_read_b128 v[156:159], v151 offset:1024
	ds_read_b128 v[160:163], v151 offset:2048
	ds_read_b128 v[164:167], v151 offset:3072
	v_add_u32_e32 v151, s49, v149
	s_add_u32 s28, s24, s26
	ds_read_b128 v[168:171], v151
	ds_read_b128 v[172:175], v151 offset:1024
	ds_read_b128 v[176:179], v151 offset:2048
	ds_read_b128 v[180:183], v151 offset:3072
	s_addc_u32 s29, s25, s27
	s_add_u32 s28, s28, 0x100
	s_addc_u32 s29, s29, 0
	s_add_u32 s55, s21, s26
	s_addc_u32 s56, s53, s27
	s_cmpk_eq_i32 s26, 0x2b00
	s_cselect_b32 s31, s5, s29
	s_cselect_b32 s30, s4, s28
	s_cselect_b32 s29, s23, s56
	s_cselect_b32 s28, s22, s55
	v_lshl_add_u64 v[218:219], v[144:145], 0, s[26:27]
	s_add_i32 m0, s39, 0xc000
	ds_read_b128 v[184:187], v150
	ds_read_b128 v[188:191], v150 offset:1024
	ds_read_b128 v[194:197], v150 offset:2048
	ds_read_b128 v[198:201], v150 offset:3072
	ds_read_b128 v[202:205], v150 offset:4096
	ds_read_b128 v[206:209], v150 offset:5120
	ds_read_b128 v[210:213], v150 offset:6144
	ds_read_b128 v[214:217], v150 offset:7168
	global_load_lds_dwordx4 v[218:219], off
	v_lshl_add_u64 v[218:219], v[146:147], 0, s[26:27]
	s_add_i32 m0, s39, 0xe000
	s_nop 0
	global_load_lds_dwordx4 v[218:219], off
	s_waitcnt vmcnt(8)
	s_waitcnt lgkmcnt(0)
	s_barrier
	s_waitcnt lgkmcnt(0)
	v_mfma_f32_16x16x32_bf16 v[124:127], v[152:155], v[184:187], v[124:127]
	v_mfma_f32_16x16x32_bf16 v[120:123], v[160:163], v[184:187], v[120:123]
	v_mfma_f32_16x16x32_bf16 v[104:107], v[160:163], v[194:197], v[104:107]
	v_mfma_f32_16x16x32_bf16 v[108:111], v[152:155], v[194:197], v[108:111]
	v_mfma_f32_16x16x32_bf16 v[92:95], v[152:155], v[202:205], v[92:95]
	v_mfma_f32_16x16x32_bf16 v[88:91], v[160:163], v[202:205], v[88:91]
	v_mfma_f32_16x16x32_bf16 v[72:75], v[160:163], v[210:213], v[72:75]
	v_mfma_f32_16x16x32_bf16 v[76:79], v[152:155], v[210:213], v[76:79]
	v_mfma_f32_16x16x32_bf16 v[124:127], v[156:159], v[188:191], v[124:127]
	v_mfma_f32_16x16x32_bf16 v[120:123], v[164:167], v[188:191], v[120:123]
	v_mfma_f32_16x16x32_bf16 v[104:107], v[164:167], v[198:201], v[104:107]
	v_mfma_f32_16x16x32_bf16 v[108:111], v[156:159], v[198:201], v[108:111]
	v_mfma_f32_16x16x32_bf16 v[92:95], v[156:159], v[206:209], v[92:95]
	v_mfma_f32_16x16x32_bf16 v[88:91], v[164:167], v[206:209], v[88:91]
	v_mfma_f32_16x16x32_bf16 v[72:75], v[164:167], v[214:217], v[72:75]
	v_mfma_f32_16x16x32_bf16 v[76:79], v[156:159], v[214:217], v[76:79]
	v_mfma_f32_16x16x32_bf16 v[116:119], v[168:171], v[184:187], v[116:119]
	v_mfma_f32_16x16x32_bf16 v[112:115], v[176:179], v[184:187], v[112:115]
	v_mfma_f32_16x16x32_bf16 v[96:99], v[176:179], v[194:197], v[96:99]
	v_mfma_f32_16x16x32_bf16 v[100:103], v[168:171], v[194:197], v[100:103]
	v_mfma_f32_16x16x32_bf16 v[84:87], v[168:171], v[202:205], v[84:87]
	v_mfma_f32_16x16x32_bf16 v[80:83], v[176:179], v[202:205], v[80:83]
	v_mfma_f32_16x16x32_bf16 v[64:67], v[176:179], v[210:213], v[64:67]
	v_mfma_f32_16x16x32_bf16 v[68:71], v[168:171], v[210:213], v[68:71]
	v_mfma_f32_16x16x32_bf16 v[116:119], v[172:175], v[188:191], v[116:119]
	v_mfma_f32_16x16x32_bf16 v[112:115], v[180:183], v[188:191], v[112:115]
	v_mfma_f32_16x16x32_bf16 v[96:99], v[180:183], v[198:201], v[96:99]
	v_mfma_f32_16x16x32_bf16 v[100:103], v[172:175], v[198:201], v[100:103]
	v_mfma_f32_16x16x32_bf16 v[84:87], v[172:175], v[206:209], v[84:87]
	v_mfma_f32_16x16x32_bf16 v[80:83], v[180:183], v[206:209], v[80:83]
	v_mfma_f32_16x16x32_bf16 v[64:67], v[180:183], v[214:217], v[64:67]
	v_mfma_f32_16x16x32_bf16 v[68:71], v[172:175], v[214:217], v[68:71]
	s_barrier
	s_add_i32 s55, s48, s38
	v_lshl_add_u64 v[218:219], s[28:29], 0, v[130:131]
	s_mov_b32 m0, s55
	ds_read_b128 v[184:187], v150 offset:16384
	ds_read_b128 v[188:191], v150 offset:17408
	ds_read_b128 v[194:197], v150 offset:18432
	ds_read_b128 v[198:201], v150 offset:19456
	ds_read_b128 v[202:205], v150 offset:20480
	ds_read_b128 v[206:209], v150 offset:21504
	ds_read_b128 v[210:213], v150 offset:22528
	ds_read_b128 v[214:217], v150 offset:23552
	global_load_lds_dwordx4 v[218:219], off
	s_add_i32 m0, s55, 0x2000
	s_add_u32 s56, s28, 0x160000
	v_lshl_add_u64 v[220:221], s[28:29], 0, v[134:135]
	s_addc_u32 s57, s29, 0
	s_add_i32 s55, s49, s38
	global_load_lds_dwordx4 v[220:221], off
	v_lshl_add_u64 v[222:223], s[56:57], 0, v[130:131]
	s_mov_b32 m0, s55
	v_lshl_add_u64 v[224:225], s[30:31], 0, v[132:133]
	global_load_lds_dwordx4 v[222:223], off
	v_lshl_add_u64 v[222:223], s[56:57], 0, v[134:135]
	s_add_i32 m0, s55, 0x2000
	s_nop 0
	global_load_lds_dwordx4 v[222:223], off
	v_lshl_add_u64 v[222:223], s[30:31], 0, v[128:129]
	s_mov_b32 m0, s39
	s_nop 0
	global_load_lds_dwordx4 v[222:223], off
	s_mov_b32 m0, s40
	s_nop 0
	global_load_lds_dwordx4 v[224:225], off
	s_waitcnt vmcnt(8)
	s_waitcnt lgkmcnt(0)
	s_barrier
	s_waitcnt lgkmcnt(0)
	v_mfma_f32_16x16x32_bf16 v[60:63], v[152:155], v[184:187], v[60:63]
	v_mfma_f32_16x16x32_bf16 v[56:59], v[160:163], v[184:187], v[56:59]
	v_mfma_f32_16x16x32_bf16 v[40:43], v[160:163], v[194:197], v[40:43]
	v_mfma_f32_16x16x32_bf16 v[44:47], v[152:155], v[194:197], v[44:47]
	v_mfma_f32_16x16x32_bf16 v[28:31], v[152:155], v[202:205], v[28:31]
	v_mfma_f32_16x16x32_bf16 v[24:27], v[160:163], v[202:205], v[24:27]
	v_mfma_f32_16x16x32_bf16 v[8:11], v[160:163], v[210:213], v[8:11]
	v_mfma_f32_16x16x32_bf16 v[12:15], v[152:155], v[210:213], v[12:15]
	v_mfma_f32_16x16x32_bf16 v[60:63], v[156:159], v[188:191], v[60:63]
	v_mfma_f32_16x16x32_bf16 v[56:59], v[164:167], v[188:191], v[56:59]
	v_mfma_f32_16x16x32_bf16 v[40:43], v[164:167], v[198:201], v[40:43]
	v_mfma_f32_16x16x32_bf16 v[44:47], v[156:159], v[198:201], v[44:47]
	v_mfma_f32_16x16x32_bf16 v[28:31], v[156:159], v[206:209], v[28:31]
	v_mfma_f32_16x16x32_bf16 v[24:27], v[164:167], v[206:209], v[24:27]
	v_mfma_f32_16x16x32_bf16 v[8:11], v[164:167], v[214:217], v[8:11]
	v_mfma_f32_16x16x32_bf16 v[12:15], v[156:159], v[214:217], v[12:15]
	v_mfma_f32_16x16x32_bf16 v[52:55], v[168:171], v[184:187], v[52:55]
	v_mfma_f32_16x16x32_bf16 v[48:51], v[176:179], v[184:187], v[48:51]
	v_mfma_f32_16x16x32_bf16 v[32:35], v[176:179], v[194:197], v[32:35]
	v_mfma_f32_16x16x32_bf16 v[36:39], v[168:171], v[194:197], v[36:39]
	v_mfma_f32_16x16x32_bf16 v[20:23], v[168:171], v[202:205], v[20:23]
	v_mfma_f32_16x16x32_bf16 v[16:19], v[176:179], v[202:205], v[16:19]
	v_mfma_f32_16x16x32_bf16 v[0:3], v[176:179], v[210:213], v[0:3]
	v_mfma_f32_16x16x32_bf16 v[4:7], v[168:171], v[210:213], v[4:7]
	v_mfma_f32_16x16x32_bf16 v[52:55], v[172:175], v[188:191], v[52:55]
	v_mfma_f32_16x16x32_bf16 v[48:51], v[180:183], v[188:191], v[48:51]
	v_mfma_f32_16x16x32_bf16 v[32:35], v[180:183], v[198:201], v[32:35]
	v_mfma_f32_16x16x32_bf16 v[36:39], v[172:175], v[198:201], v[36:39]
	v_mfma_f32_16x16x32_bf16 v[20:23], v[172:175], v[206:209], v[20:23]
	v_mfma_f32_16x16x32_bf16 v[16:19], v[180:183], v[206:209], v[16:19]
	v_mfma_f32_16x16x32_bf16 v[0:3], v[180:183], v[214:217], v[0:3]
	v_mfma_f32_16x16x32_bf16 v[4:7], v[172:175], v[214:217], v[4:7]
	s_barrier
	s_add_i32 s55, 0, 0x18000
	v_add_u32_e32 v151, s55, v149
	s_add_i32 s56, 0, 0x1c000
	ds_read_b128 v[152:155], v151
	ds_read_b128 v[156:159], v151 offset:1024
	ds_read_b128 v[160:163], v151 offset:2048
	ds_read_b128 v[164:167], v151 offset:3072
	v_add_u32_e32 v151, s56, v149
	ds_read_b128 v[168:171], v151
	ds_read_b128 v[172:175], v151 offset:1024
	ds_read_b128 v[176:179], v151 offset:2048
	ds_read_b128 v[180:183], v151 offset:3072
	s_add_u32 s30, s30, 0x160000
	s_addc_u32 s31, s31, 0
	s_mov_b32 m0, s41
	v_lshl_add_u64 v[226:227], s[30:31], 0, v[128:129]
	ds_read_b128 v[184:187], v150 offset:32768
	ds_read_b128 v[188:191], v150 offset:33792
	ds_read_b128 v[194:197], v150 offset:34816
	ds_read_b128 v[198:201], v150 offset:35840
	ds_read_b128 v[202:205], v150 offset:36864
	ds_read_b128 v[206:209], v150 offset:37888
	ds_read_b128 v[210:213], v150 offset:38912
	ds_read_b128 v[214:217], v150 offset:39936
	global_load_lds_dwordx4 v[226:227], off
	v_lshl_add_u64 v[226:227], s[30:31], 0, v[132:133]
	s_mov_b32 m0, s42
	s_nop 0
	global_load_lds_dwordx4 v[226:227], off
	s_waitcnt vmcnt(8)
	s_waitcnt lgkmcnt(0)
	s_barrier
	s_waitcnt lgkmcnt(0)
	v_mfma_f32_16x16x32_bf16 v[124:127], v[152:155], v[184:187], v[124:127]
	v_mfma_f32_16x16x32_bf16 v[120:123], v[160:163], v[184:187], v[120:123]
	v_mfma_f32_16x16x32_bf16 v[104:107], v[160:163], v[194:197], v[104:107]
	v_mfma_f32_16x16x32_bf16 v[108:111], v[152:155], v[194:197], v[108:111]
	v_mfma_f32_16x16x32_bf16 v[92:95], v[152:155], v[202:205], v[92:95]
	v_mfma_f32_16x16x32_bf16 v[88:91], v[160:163], v[202:205], v[88:91]
	v_mfma_f32_16x16x32_bf16 v[72:75], v[160:163], v[210:213], v[72:75]
	v_mfma_f32_16x16x32_bf16 v[76:79], v[152:155], v[210:213], v[76:79]
	v_mfma_f32_16x16x32_bf16 v[124:127], v[156:159], v[188:191], v[124:127]
	v_mfma_f32_16x16x32_bf16 v[120:123], v[164:167], v[188:191], v[120:123]
	v_mfma_f32_16x16x32_bf16 v[104:107], v[164:167], v[198:201], v[104:107]
	v_mfma_f32_16x16x32_bf16 v[108:111], v[156:159], v[198:201], v[108:111]
	v_mfma_f32_16x16x32_bf16 v[92:95], v[156:159], v[206:209], v[92:95]
	v_mfma_f32_16x16x32_bf16 v[88:91], v[164:167], v[206:209], v[88:91]
	v_mfma_f32_16x16x32_bf16 v[72:75], v[164:167], v[214:217], v[72:75]
	v_mfma_f32_16x16x32_bf16 v[76:79], v[156:159], v[214:217], v[76:79]
	v_mfma_f32_16x16x32_bf16 v[116:119], v[168:171], v[184:187], v[116:119]
	v_mfma_f32_16x16x32_bf16 v[112:115], v[176:179], v[184:187], v[112:115]
	v_mfma_f32_16x16x32_bf16 v[96:99], v[176:179], v[194:197], v[96:99]
	v_mfma_f32_16x16x32_bf16 v[100:103], v[168:171], v[194:197], v[100:103]
	v_mfma_f32_16x16x32_bf16 v[84:87], v[168:171], v[202:205], v[84:87]
	v_mfma_f32_16x16x32_bf16 v[80:83], v[176:179], v[202:205], v[80:83]
	v_mfma_f32_16x16x32_bf16 v[64:67], v[176:179], v[210:213], v[64:67]
	v_mfma_f32_16x16x32_bf16 v[68:71], v[168:171], v[210:213], v[68:71]
	v_mfma_f32_16x16x32_bf16 v[116:119], v[172:175], v[188:191], v[116:119]
	v_mfma_f32_16x16x32_bf16 v[112:115], v[180:183], v[188:191], v[112:115]
	v_mfma_f32_16x16x32_bf16 v[96:99], v[180:183], v[198:201], v[96:99]
	v_mfma_f32_16x16x32_bf16 v[100:103], v[172:175], v[198:201], v[100:103]
	v_mfma_f32_16x16x32_bf16 v[84:87], v[172:175], v[206:209], v[84:87]
	v_mfma_f32_16x16x32_bf16 v[80:83], v[180:183], v[206:209], v[80:83]
	v_mfma_f32_16x16x32_bf16 v[64:67], v[180:183], v[214:217], v[64:67]
	v_mfma_f32_16x16x32_bf16 v[68:71], v[172:175], v[214:217], v[68:71]
	s_barrier
	s_add_i32 s30, s55, s38
	v_lshl_add_u64 v[218:219], v[218:219], 0, s[16:17]
	s_mov_b32 m0, s30
	ds_read_b128 v[184:187], v150 offset:49152
	ds_read_b128 v[188:191], v150 offset:50176
	ds_read_b128 v[194:197], v150 offset:51200
	ds_read_b128 v[198:201], v150 offset:52224
	ds_read_b128 v[202:205], v150 offset:53248
	ds_read_b128 v[206:209], v150 offset:54272
	ds_read_b128 v[210:213], v150 offset:55296
	ds_read_b128 v[214:217], v150 offset:56320
	global_load_lds_dwordx4 v[218:219], off
	s_add_i32 m0, s30, 0x2000
	s_add_u32 s28, s28, 0x160080
	v_lshl_add_u64 v[218:219], v[220:221], 0, s[16:17]
	s_addc_u32 s29, s29, 0
	s_add_i32 s30, s56, s38
	global_load_lds_dwordx4 v[218:219], off
	v_lshl_add_u64 v[218:219], s[28:29], 0, v[130:131]
	s_mov_b32 m0, s30
	s_nop 0
	global_load_lds_dwordx4 v[218:219], off
	v_lshl_add_u64 v[218:219], s[28:29], 0, v[134:135]
	s_add_i32 m0, s30, 0x2000
	s_nop 0
	global_load_lds_dwordx4 v[218:219], off
	v_lshl_add_u64 v[218:219], v[222:223], 0, s[16:17]
	s_mov_b32 m0, s45
	s_nop 0
	global_load_lds_dwordx4 v[218:219], off
	v_lshl_add_u64 v[218:219], v[224:225], 0, s[16:17]
	s_mov_b32 m0, s46
	s_nop 0
	global_load_lds_dwordx4 v[218:219], off
	s_waitcnt vmcnt(8)
	s_waitcnt lgkmcnt(0)
	s_barrier
	s_waitcnt lgkmcnt(0)
	v_mfma_f32_16x16x32_bf16 v[60:63], v[152:155], v[184:187], v[60:63]
	v_mfma_f32_16x16x32_bf16 v[56:59], v[160:163], v[184:187], v[56:59]
	v_mfma_f32_16x16x32_bf16 v[40:43], v[160:163], v[194:197], v[40:43]
	v_mfma_f32_16x16x32_bf16 v[44:47], v[152:155], v[194:197], v[44:47]
	v_mfma_f32_16x16x32_bf16 v[28:31], v[152:155], v[202:205], v[28:31]
	v_mfma_f32_16x16x32_bf16 v[24:27], v[160:163], v[202:205], v[24:27]
	v_mfma_f32_16x16x32_bf16 v[8:11], v[160:163], v[210:213], v[8:11]
	v_mfma_f32_16x16x32_bf16 v[12:15], v[152:155], v[210:213], v[12:15]
	v_mfma_f32_16x16x32_bf16 v[60:63], v[156:159], v[188:191], v[60:63]
	v_mfma_f32_16x16x32_bf16 v[56:59], v[164:167], v[188:191], v[56:59]
	v_mfma_f32_16x16x32_bf16 v[40:43], v[164:167], v[198:201], v[40:43]
	v_mfma_f32_16x16x32_bf16 v[44:47], v[156:159], v[198:201], v[44:47]
	v_mfma_f32_16x16x32_bf16 v[28:31], v[156:159], v[206:209], v[28:31]
	v_mfma_f32_16x16x32_bf16 v[24:27], v[164:167], v[206:209], v[24:27]
	v_mfma_f32_16x16x32_bf16 v[8:11], v[164:167], v[214:217], v[8:11]
	v_mfma_f32_16x16x32_bf16 v[12:15], v[156:159], v[214:217], v[12:15]
	v_mfma_f32_16x16x32_bf16 v[52:55], v[168:171], v[184:187], v[52:55]
	v_mfma_f32_16x16x32_bf16 v[48:51], v[176:179], v[184:187], v[48:51]
	v_mfma_f32_16x16x32_bf16 v[32:35], v[176:179], v[194:197], v[32:35]
	v_mfma_f32_16x16x32_bf16 v[36:39], v[168:171], v[194:197], v[36:39]
	v_mfma_f32_16x16x32_bf16 v[20:23], v[168:171], v[202:205], v[20:23]
	v_mfma_f32_16x16x32_bf16 v[16:19], v[176:179], v[202:205], v[16:19]
	v_mfma_f32_16x16x32_bf16 v[0:3], v[176:179], v[210:213], v[0:3]
	v_mfma_f32_16x16x32_bf16 v[4:7], v[168:171], v[210:213], v[4:7]
	v_mfma_f32_16x16x32_bf16 v[52:55], v[172:175], v[188:191], v[52:55]
	v_mfma_f32_16x16x32_bf16 v[48:51], v[180:183], v[188:191], v[48:51]
	v_mfma_f32_16x16x32_bf16 v[32:35], v[180:183], v[198:201], v[32:35]
	v_mfma_f32_16x16x32_bf16 v[36:39], v[172:175], v[198:201], v[36:39]
	v_mfma_f32_16x16x32_bf16 v[20:23], v[172:175], v[206:209], v[20:23]
	v_mfma_f32_16x16x32_bf16 v[16:19], v[180:183], v[206:209], v[16:19]
	v_mfma_f32_16x16x32_bf16 v[0:3], v[180:183], v[214:217], v[0:3]
	v_mfma_f32_16x16x32_bf16 v[4:7], v[172:175], v[214:217], v[4:7]
	s_barrier
	s_add_i32 s54, s54, 2
	s_add_u32 s26, s26, 0x100
	s_addc_u32 s27, s27, 0
	s_cmpk_gt_u32 s54, 0x55
	s_cbranch_scc0 .LBB0_2113
	s_and_b64 vcc, exec, s[18:19]
	s_cbranch_vccz .LBB0_2116
	s_barrier
